# late transposes in phase-2 tail with write-through (sc0 sc1) stores, no in-proj stagger
# speedup vs baseline: 1.0033x; 1.0033x over previous
.Lmy_lt_77:
	s_waitcnt lgkmcnt(0)
	ds_read2_b32 v[30:31], v48 offset1:33
	s_waitcnt lgkmcnt(0)
	v_cvt_pk_bf16_f32 v30, v30, v31
	ds_read2_b32 v[32:33], v48 offset0:66 offset1:99
	s_waitcnt lgkmcnt(0)
	v_cvt_pk_bf16_f32 v31, v32, v33
	ds_read2_b32 v[32:33], v48 offset0:132 offset1:165
	v_or_b32_e32 v36, v3, v47
	s_waitcnt lgkmcnt(0)
	v_cvt_pk_bf16_f32 v32, v32, v33
	ds_read2_b32 v[34:35], v48 offset0:198 offset1:231
	v_ashrrev_i32_e32 v29, 31, v28
	v_ashrrev_i32_e32 v37, 31, v36
	v_lshl_add_u64 v[38:39], v[28:29], 1, v[26:27]
	s_waitcnt lgkmcnt(0)
	v_cvt_pk_bf16_f32 v33, v34, v35
	v_lshlrev_b64 v[34:35], 11, v[36:37]
	v_lshl_add_u64 v[34:35], v[38:39], 0, v[34:35]
	global_store_dwordx4 v[34:35], v[30:33], off sc0 sc1
	v_or_b32_e32 v34, v3, v49
	ds_read2_b32 v[28:29], v48 offset0:8 offset1:41
	v_ashrrev_i32_e32 v35, 31, v34
	s_waitcnt lgkmcnt(0)
	v_cvt_pk_bf16_f32 v28, v28, v29
	ds_read2_b32 v[30:31], v48 offset0:74 offset1:107
	v_lshlrev_b64 v[34:35], 11, v[34:35]
	s_waitcnt lgkmcnt(0)
	v_cvt_pk_bf16_f32 v29, v30, v31
	ds_read2_b32 v[30:31], v48 offset0:140 offset1:173
	v_lshl_add_u64 v[34:35], v[38:39], 0, v[34:35]
	s_waitcnt lgkmcnt(0)
	v_cvt_pk_bf16_f32 v30, v30, v31
	ds_read2_b32 v[32:33], v48 offset0:206 offset1:239
	s_waitcnt lgkmcnt(0)
	v_cvt_pk_bf16_f32 v31, v32, v33
	global_store_dwordx4 v[34:35], v[28:31], off sc0 sc1
	v_or_b32_e32 v34, v3, v50
	ds_read2_b32 v[32:33], v48 offset0:16 offset1:49
	s_waitcnt lgkmcnt(0)
	v_cvt_pk_bf16_f32 v28, v32, v33
	ds_read2_b32 v[30:31], v48 offset0:82 offset1:115
	v_ashrrev_i32_e32 v35, 31, v34
	s_waitcnt lgkmcnt(0)
	v_cvt_pk_bf16_f32 v29, v30, v31
	ds_read2_b32 v[30:31], v48 offset0:148 offset1:181
	v_lshlrev_b64 v[34:35], 11, v[34:35]
	s_waitcnt lgkmcnt(0)
	v_cvt_pk_bf16_f32 v30, v30, v31
	ds_read2_b32 v[32:33], v48 offset0:214 offset1:247
	s_waitcnt lgkmcnt(0)
	v_cvt_pk_bf16_f32 v31, v32, v33
	v_lshl_add_u64 v[34:35], v[38:39], 0, v[34:35]
	ds_read2_b32 v[32:33], v48 offset0:24 offset1:57
	global_store_dwordx4 v[34:35], v[28:31], off sc0 sc1
	v_or_b32_e32 v34, v3, v51
	v_ashrrev_i32_e32 v35, 31, v34
	s_waitcnt lgkmcnt(0)
	v_cvt_pk_bf16_f32 v28, v32, v33
	ds_read2_b32 v[30:31], v48 offset0:90 offset1:123
	s_waitcnt lgkmcnt(0)
	v_cvt_pk_bf16_f32 v29, v30, v31
	ds_read2_b32 v[30:31], v48 offset0:156 offset1:189
	s_waitcnt lgkmcnt(0)
	v_cvt_pk_bf16_f32 v30, v30, v31
	ds_read2_b32 v[32:33], v48 offset0:222 offset1:255
	v_lshlrev_b64 v[34:35], 11, v[34:35]
	s_waitcnt lgkmcnt(0)
	v_cvt_pk_bf16_f32 v31, v32, v33
	v_lshl_add_u64 v[32:33], v[38:39], 0, v[34:35]
	global_store_dwordx4 v[32:33], v[28:31], off sc0 sc1
	s_waitcnt lgkmcnt(0)

.Lmy_lt_89:

	s_lshl_b32 s43, s40, 1
	s_lshl_b32 s42, s39, 1
	v_or_b32_e32 v6, s43, v30
	s_add_i32 s45, s43, 4
	s_add_i32 s44, s42, 4
	s_add_i32 s46, s42, 8
	s_add_i32 s47, s43, 8
	v_lshlrev_b64 v[70:71], 12, v[6:7]
	v_or_b32_e32 v6, s45, v30
	v_mov_b32_e32 v35, v7
	v_mov_b32_e32 v37, v7
	v_mov_b32_e32 v39, v7
	v_or_b32_e32 v34, s42, v3
	s_add_i32 s48, s42, 12
	s_add_i32 s49, s43, 12
	s_add_i32 s50, s42, 16
	s_add_i32 s52, s42, 20
	s_add_i32 s54, s42, 24
	s_add_i32 s56, s42, 28
	v_or_b32_e32 v36, s44, v3
	v_or_b32_e32 v38, s46, v3
	v_lshlrev_b64 v[72:73], 12, v[6:7]
	v_or_b32_e32 v6, s47, v30
	v_mov_b32_e32 v41, v7
	v_mov_b32_e32 v43, v7
	v_mov_b32_e32 v45, v7
	v_mov_b32_e32 v67, v7
	v_mov_b32_e32 v69, v7
	s_add_i32 s51, s43, 16
	v_lshlrev_b64 v[34:35], 12, v[34:35]
	v_or_b32_e32 v40, s48, v3
	v_or_b32_e32 v42, s50, v3
	v_or_b32_e32 v44, s52, v3
	v_or_b32_e32 v66, s54, v3
	v_or_b32_e32 v68, s56, v3
	v_lshl_add_u64 v[70:71], v[28:29], 0, v[70:71]
	v_lshlrev_b64 v[36:37], 12, v[36:37]
	v_lshlrev_b64 v[38:39], 12, v[38:39]
	v_lshlrev_b64 v[74:75], 12, v[6:7]
	v_or_b32_e32 v6, s49, v30
	s_add_i32 s53, s43, 20
	v_lshl_add_u64 v[34:35], v[28:29], 0, v[34:35]
	v_lshlrev_b64 v[40:41], 12, v[40:41]
	v_lshlrev_b64 v[42:43], 12, v[42:43]
	v_lshlrev_b64 v[44:45], 12, v[44:45]
	v_lshlrev_b64 v[66:67], 12, v[66:67]
	v_lshlrev_b64 v[68:69], 12, v[68:69]
	v_lshl_add_u64 v[72:73], v[28:29], 0, v[72:73]
	v_lshl_add_u64 v[36:37], v[28:29], 0, v[36:37]
	v_lshl_add_u64 v[38:39], v[28:29], 0, v[38:39]
	global_load_dword v33, v[70:71], off
	global_load_dword v65, v[34:35], off
	v_lshlrev_b64 v[70:71], 12, v[6:7]
	v_or_b32_e32 v6, s51, v30
	s_add_i32 s55, s43, 24
	v_lshl_add_u64 v[40:41], v[28:29], 0, v[40:41]
	v_lshl_add_u64 v[42:43], v[28:29], 0, v[42:43]
	v_lshl_add_u64 v[44:45], v[28:29], 0, v[44:45]
	v_lshl_add_u64 v[66:67], v[28:29], 0, v[66:67]
	v_lshl_add_u64 v[68:69], v[28:29], 0, v[68:69]
	global_load_dword v86, v[72:73], off
	global_load_dword v87, v[36:37], off
	global_load_dword v88, v[38:39], off
	global_load_dword v89, v[40:41], off
	global_load_dword v90, v[42:43], off
	global_load_dword v91, v[44:45], off
	global_load_dword v92, v[66:67], off
	global_load_dword v93, v[68:69], off
	v_lshl_add_u64 v[36:37], v[28:29], 0, v[70:71]
	v_lshlrev_b64 v[38:39], 12, v[6:7]
	v_or_b32_e32 v6, s53, v30
	s_add_i32 s57, s43, 28
	v_lshl_add_u64 v[34:35], v[28:29], 0, v[74:75]
	global_load_dword v94, v[36:37], off
	global_load_dword v95, v[34:35], off
	v_lshlrev_b64 v[36:37], 12, v[6:7]
	v_or_b32_e32 v6, s55, v30
	v_lshl_add_u64 v[34:35], v[28:29], 0, v[38:39]
	v_lshlrev_b64 v[38:39], 12, v[6:7]
	v_or_b32_e32 v6, s57, v30
	v_lshlrev_b64 v[40:41], 12, v[6:7]
	v_lshl_add_u64 v[40:41], v[28:29], 0, v[40:41]
	v_lshl_add_u64 v[36:37], v[28:29], 0, v[36:37]
	v_lshl_add_u64 v[38:39], v[28:29], 0, v[38:39]
	global_load_dword v6, v[40:41], off
	global_load_dword v96, v[38:39], off
	global_load_dword v97, v[36:37], off
	global_load_dword v98, v[34:35], off
	v_or_b32_e32 v36, s42, v1
	v_or_b32_e32 v34, s43, v2
	s_add_i32 s40, s40, 16
	s_add_i32 s39, s39, 16
	s_add_i32 s41, s41, -16
	v_mad_u64_u32 v[34:35], s[42:43], v34, s25, v[4:5]
	v_mad_u64_u32 v[36:37], s[42:43], v36, s25, v[4:5]
	v_or_b32_e32 v35, s44, v1
	v_or_b32_e32 v37, s45, v2
	v_or_b32_e32 v44, s46, v1
	v_or_b32_e32 v42, s47, v2
	v_or_b32_e32 v68, s48, v1
	v_or_b32_e32 v66, s49, v2
	v_or_b32_e32 v72, s50, v1
	v_or_b32_e32 v70, s51, v2
	v_or_b32_e32 v76, s52, v1
	v_or_b32_e32 v74, s53, v2
	v_or_b32_e32 v80, s54, v1
	v_or_b32_e32 v78, s55, v2
	v_or_b32_e32 v84, s56, v1
	v_or_b32_e32 v82, s57, v2
	s_cmp_lg_u32 s41, 0
	v_mad_u64_u32 v[38:39], s[42:43], v37, s25, v[4:5]
	v_mad_u64_u32 v[40:41], s[42:43], v35, s25, v[4:5]
	v_mad_u64_u32 v[42:43], s[42:43], v42, s25, v[4:5]
	v_mad_u64_u32 v[44:45], s[42:43], v44, s25, v[4:5]
	v_mad_u64_u32 v[66:67], s[42:43], v66, s25, v[4:5]
	v_mad_u64_u32 v[68:69], s[42:43], v68, s25, v[4:5]
	v_mad_u64_u32 v[70:71], s[42:43], v70, s25, v[4:5]
	v_mad_u64_u32 v[72:73], s[42:43], v72, s25, v[4:5]
	v_mad_u64_u32 v[74:75], s[42:43], v74, s25, v[4:5]
	v_mad_u64_u32 v[76:77], s[42:43], v76, s25, v[4:5]
	v_mad_u64_u32 v[78:79], s[42:43], v78, s25, v[4:5]
	v_mad_u64_u32 v[80:81], s[42:43], v80, s25, v[4:5]
	v_mad_u64_u32 v[82:83], s[42:43], v82, s25, v[4:5]
	v_mad_u64_u32 v[84:85], s[42:43], v84, s25, v[4:5]
	s_waitcnt vmcnt(15)
	ds_write_b32 v34, v33
	s_waitcnt vmcnt(14)
	ds_write_b32 v36, v65
	s_waitcnt vmcnt(13)
	ds_write_b32 v38, v86
	s_waitcnt vmcnt(12)
	ds_write_b32 v40, v87
	s_waitcnt vmcnt(4)
	ds_write_b32 v42, v95
	ds_write_b32 v44, v88
	ds_write_b32 v66, v94
	ds_write_b32 v68, v89
	s_waitcnt vmcnt(0)
	ds_write_b32 v70, v98
	ds_write_b32 v72, v90
	ds_write_b32 v74, v97
	ds_write_b32 v76, v91
	ds_write_b32 v78, v96
	ds_write_b32 v80, v92
	ds_write_b32 v82, v6
	ds_write_b32 v84, v93
	s_cbranch_scc1 .Lmy_lt_89

	s_waitcnt lgkmcnt(0)
	ds_read2_b32 v[28:29], v48 offset1:33
	s_waitcnt lgkmcnt(0)
	v_cvt_pk_bf16_f32 v34, v28, v29
	ds_read2_b32 v[28:29], v48 offset0:66 offset1:99
	s_waitcnt lgkmcnt(0)
	v_cvt_pk_bf16_f32 v35, v28, v29
	ds_read2_b32 v[28:29], v48 offset0:132 offset1:165
	v_lshlrev_b32_e32 v6, 1, v32
	v_or_b32_e32 v3, v31, v47
	s_waitcnt lgkmcnt(0)
	v_cvt_pk_bf16_f32 v36, v28, v29
	ds_read2_b32 v[28:29], v48 offset0:198 offset1:231
	v_lshl_add_u64 v[38:39], v[8:9], 0, v[6:7]
	v_lshlrev_b32_e32 v6, 12, v3
	s_waitcnt lgkmcnt(0)
	v_cvt_pk_bf16_f32 v37, v28, v29
	ds_read2_b32 v[28:29], v48 offset0:8 offset1:41
	v_lshl_add_u64 v[32:33], v[38:39], 0, v[6:7]
	global_store_dwordx4 v[32:33], v[34:37], off sc0 sc1
	s_waitcnt lgkmcnt(0)
	v_cvt_pk_bf16_f32 v32, v28, v29
	ds_read2_b32 v[28:29], v48 offset0:74 offset1:107
	s_waitcnt lgkmcnt(0)
	v_cvt_pk_bf16_f32 v33, v28, v29
	ds_read2_b32 v[28:29], v48 offset0:140 offset1:173
	v_or_b32_e32 v3, v31, v49
	s_waitcnt lgkmcnt(0)
	v_cvt_pk_bf16_f32 v34, v28, v29
	ds_read2_b32 v[28:29], v48 offset0:206 offset1:239
	v_lshlrev_b32_e32 v6, 12, v3
	s_waitcnt lgkmcnt(0)
	v_cvt_pk_bf16_f32 v35, v28, v29
	ds_read2_b32 v[28:29], v48 offset0:16 offset1:49
	v_lshl_add_u64 v[36:37], v[38:39], 0, v[6:7]
	global_store_dwordx4 v[36:37], v[32:35], off sc0 sc1
	v_or_b32_e32 v3, v31, v50
	v_lshlrev_b32_e32 v6, 12, v3
	s_waitcnt lgkmcnt(0)
	v_cvt_pk_bf16_f32 v32, v28, v29
	ds_read2_b32 v[28:29], v48 offset0:82 offset1:115
	s_waitcnt lgkmcnt(0)
	v_cvt_pk_bf16_f32 v33, v28, v29
	ds_read2_b32 v[28:29], v48 offset0:148 offset1:181
	s_waitcnt lgkmcnt(0)
	v_cvt_pk_bf16_f32 v34, v28, v29
	ds_read2_b32 v[28:29], v48 offset0:214 offset1:247
	s_waitcnt lgkmcnt(0)
	v_cvt_pk_bf16_f32 v35, v28, v29
	ds_read2_b32 v[28:29], v48 offset0:24 offset1:57
	v_lshl_add_u64 v[36:37], v[38:39], 0, v[6:7]
	global_store_dwordx4 v[36:37], v[32:35], off sc0 sc1
	s_waitcnt lgkmcnt(0)
	v_cvt_pk_bf16_f32 v28, v28, v29
	ds_read2_b32 v[32:33], v48 offset0:90 offset1:123
	s_waitcnt lgkmcnt(0)
	v_cvt_pk_bf16_f32 v29, v32, v33
	ds_read2_b32 v[32:33], v48 offset0:156 offset1:189
	v_or_b32_e32 v3, v31, v51
	s_waitcnt lgkmcnt(0)
	v_cvt_pk_bf16_f32 v30, v32, v33
	ds_read2_b32 v[32:33], v48 offset0:222 offset1:255
	v_lshlrev_b32_e32 v6, 12, v3
	s_waitcnt lgkmcnt(0)
	v_cvt_pk_bf16_f32 v31, v32, v33
	v_lshl_add_u64 v[32:33], v[38:39], 0, v[6:7]
	global_store_dwordx4 v[32:33], v[28:31], off sc0 sc1
	s_waitcnt lgkmcnt(0)

.Lmy_lt_93:

	s_lshl_b32 s43, s40, 1
	s_lshl_b32 s42, s39, 1
	v_or_b32_e32 v6, s43, v30
	s_add_i32 s45, s43, 4
	s_add_i32 s44, s42, 4
	s_add_i32 s46, s42, 8
	s_add_i32 s47, s43, 8
	v_lshlrev_b64 v[70:71], 12, v[6:7]
	v_or_b32_e32 v6, s45, v30
	v_mov_b32_e32 v35, v7
	v_mov_b32_e32 v37, v7
	v_mov_b32_e32 v39, v7
	v_or_b32_e32 v34, s42, v3
	s_add_i32 s48, s42, 12
	s_add_i32 s49, s43, 12
	s_add_i32 s50, s42, 16
	s_add_i32 s52, s42, 20
	s_add_i32 s54, s42, 24
	s_add_i32 s56, s42, 28
	v_or_b32_e32 v36, s44, v3
	v_or_b32_e32 v38, s46, v3
	v_lshlrev_b64 v[72:73], 12, v[6:7]
	v_or_b32_e32 v6, s47, v30
	v_mov_b32_e32 v41, v7
	v_mov_b32_e32 v43, v7
	v_mov_b32_e32 v45, v7
	v_mov_b32_e32 v67, v7
	v_mov_b32_e32 v69, v7
	s_add_i32 s51, s43, 16
	v_lshlrev_b64 v[34:35], 12, v[34:35]
	v_or_b32_e32 v40, s48, v3
	v_or_b32_e32 v42, s50, v3
	v_or_b32_e32 v44, s52, v3
	v_or_b32_e32 v66, s54, v3
	v_or_b32_e32 v68, s56, v3
	v_lshl_add_u64 v[70:71], v[28:29], 0, v[70:71]
	v_lshlrev_b64 v[36:37], 12, v[36:37]
	v_lshlrev_b64 v[38:39], 12, v[38:39]
	v_lshlrev_b64 v[74:75], 12, v[6:7]
	v_or_b32_e32 v6, s49, v30
	s_add_i32 s53, s43, 20
	v_lshl_add_u64 v[34:35], v[28:29], 0, v[34:35]
	v_lshlrev_b64 v[40:41], 12, v[40:41]
	v_lshlrev_b64 v[42:43], 12, v[42:43]
	v_lshlrev_b64 v[44:45], 12, v[44:45]
	v_lshlrev_b64 v[66:67], 12, v[66:67]
	v_lshlrev_b64 v[68:69], 12, v[68:69]
	v_lshl_add_u64 v[72:73], v[28:29], 0, v[72:73]
	v_lshl_add_u64 v[36:37], v[28:29], 0, v[36:37]
	v_lshl_add_u64 v[38:39], v[28:29], 0, v[38:39]
	global_load_dword v33, v[70:71], off
	global_load_dword v65, v[34:35], off
	v_lshlrev_b64 v[70:71], 12, v[6:7]
	v_or_b32_e32 v6, s51, v30
	s_add_i32 s55, s43, 24
	v_lshl_add_u64 v[40:41], v[28:29], 0, v[40:41]
	v_lshl_add_u64 v[42:43], v[28:29], 0, v[42:43]
	v_lshl_add_u64 v[44:45], v[28:29], 0, v[44:45]
	v_lshl_add_u64 v[66:67], v[28:29], 0, v[66:67]
	v_lshl_add_u64 v[68:69], v[28:29], 0, v[68:69]
	global_load_dword v86, v[72:73], off
	global_load_dword v87, v[36:37], off
	global_load_dword v88, v[38:39], off
	global_load_dword v89, v[40:41], off
	global_load_dword v90, v[42:43], off
	global_load_dword v91, v[44:45], off
	global_load_dword v92, v[66:67], off
	global_load_dword v93, v[68:69], off
	v_lshl_add_u64 v[36:37], v[28:29], 0, v[70:71]
	v_lshlrev_b64 v[38:39], 12, v[6:7]
	v_or_b32_e32 v6, s53, v30
	s_add_i32 s57, s43, 28
	v_lshl_add_u64 v[34:35], v[28:29], 0, v[74:75]
	global_load_dword v94, v[36:37], off
	global_load_dword v95, v[34:35], off
	v_lshlrev_b64 v[36:37], 12, v[6:7]
	v_or_b32_e32 v6, s55, v30
	v_lshl_add_u64 v[34:35], v[28:29], 0, v[38:39]
	v_lshlrev_b64 v[38:39], 12, v[6:7]
	v_or_b32_e32 v6, s57, v30
	v_lshlrev_b64 v[40:41], 12, v[6:7]
	v_lshl_add_u64 v[40:41], v[28:29], 0, v[40:41]
	v_lshl_add_u64 v[36:37], v[28:29], 0, v[36:37]
	v_lshl_add_u64 v[38:39], v[28:29], 0, v[38:39]
	global_load_dword v6, v[40:41], off
	global_load_dword v96, v[38:39], off
	global_load_dword v97, v[36:37], off
	global_load_dword v98, v[34:35], off
	v_or_b32_e32 v36, s42, v1
	v_or_b32_e32 v34, s43, v2
	s_add_i32 s40, s40, 16
	s_add_i32 s39, s39, 16
	s_add_i32 s41, s41, -16
	v_mad_u64_u32 v[34:35], s[42:43], v34, s25, v[4:5]
	v_mad_u64_u32 v[36:37], s[42:43], v36, s25, v[4:5]
	v_or_b32_e32 v35, s44, v1
	v_or_b32_e32 v37, s45, v2
	v_or_b32_e32 v44, s46, v1
	v_or_b32_e32 v42, s47, v2
	v_or_b32_e32 v68, s48, v1
	v_or_b32_e32 v66, s49, v2
	v_or_b32_e32 v72, s50, v1
	v_or_b32_e32 v70, s51, v2
	v_or_b32_e32 v76, s52, v1
	v_or_b32_e32 v74, s53, v2
	v_or_b32_e32 v80, s54, v1
	v_or_b32_e32 v78, s55, v2
	v_or_b32_e32 v84, s56, v1
	v_or_b32_e32 v82, s57, v2
	s_cmp_lg_u32 s41, 0
	v_mad_u64_u32 v[38:39], s[42:43], v37, s25, v[4:5]
	v_mad_u64_u32 v[40:41], s[42:43], v35, s25, v[4:5]
	v_mad_u64_u32 v[42:43], s[42:43], v42, s25, v[4:5]
	v_mad_u64_u32 v[44:45], s[42:43], v44, s25, v[4:5]
	v_mad_u64_u32 v[66:67], s[42:43], v66, s25, v[4:5]
	v_mad_u64_u32 v[68:69], s[42:43], v68, s25, v[4:5]
	v_mad_u64_u32 v[70:71], s[42:43], v70, s25, v[4:5]
	v_mad_u64_u32 v[72:73], s[42:43], v72, s25, v[4:5]
	v_mad_u64_u32 v[74:75], s[42:43], v74, s25, v[4:5]
	v_mad_u64_u32 v[76:77], s[42:43], v76, s25, v[4:5]
	v_mad_u64_u32 v[78:79], s[42:43], v78, s25, v[4:5]
	v_mad_u64_u32 v[80:81], s[42:43], v80, s25, v[4:5]
	v_mad_u64_u32 v[82:83], s[42:43], v82, s25, v[4:5]
	v_mad_u64_u32 v[84:85], s[42:43], v84, s25, v[4:5]
	s_waitcnt vmcnt(15)
	ds_write_b32 v34, v33
	s_waitcnt vmcnt(14)
	ds_write_b32 v36, v65
	s_waitcnt vmcnt(13)
	ds_write_b32 v38, v86
	s_waitcnt vmcnt(12)
	ds_write_b32 v40, v87
	s_waitcnt vmcnt(4)
	ds_write_b32 v42, v95
	ds_write_b32 v44, v88
	ds_write_b32 v66, v94
	ds_write_b32 v68, v89
	s_waitcnt vmcnt(0)
	ds_write_b32 v70, v98
	ds_write_b32 v72, v90
	ds_write_b32 v74, v97
	ds_write_b32 v76, v91
	ds_write_b32 v78, v96
	ds_write_b32 v80, v92
	ds_write_b32 v82, v6
	ds_write_b32 v84, v93
	s_cbranch_scc1 .Lmy_lt_93

	s_waitcnt lgkmcnt(0)
	ds_read2_b32 v[28:29], v48 offset1:33
	s_waitcnt lgkmcnt(0)
	v_cvt_pk_bf16_f32 v34, v28, v29
	ds_read2_b32 v[28:29], v48 offset0:66 offset1:99
	s_waitcnt lgkmcnt(0)
	v_cvt_pk_bf16_f32 v35, v28, v29
	ds_read2_b32 v[28:29], v48 offset0:132 offset1:165
	v_lshlrev_b32_e32 v6, 1, v32
	v_or_b32_e32 v3, v31, v47
	s_waitcnt lgkmcnt(0)
	v_cvt_pk_bf16_f32 v36, v28, v29
	ds_read2_b32 v[28:29], v48 offset0:198 offset1:231
	v_lshl_add_u64 v[38:39], v[10:11], 0, v[6:7]
	v_lshlrev_b32_e32 v6, 12, v3
	s_waitcnt lgkmcnt(0)
	v_cvt_pk_bf16_f32 v37, v28, v29
	ds_read2_b32 v[28:29], v48 offset0:8 offset1:41
	v_lshl_add_u64 v[32:33], v[38:39], 0, v[6:7]
	global_store_dwordx4 v[32:33], v[34:37], off sc0 sc1
	s_waitcnt lgkmcnt(0)
	v_cvt_pk_bf16_f32 v32, v28, v29
	ds_read2_b32 v[28:29], v48 offset0:74 offset1:107
	s_waitcnt lgkmcnt(0)
	v_cvt_pk_bf16_f32 v33, v28, v29
	ds_read2_b32 v[28:29], v48 offset0:140 offset1:173
	v_or_b32_e32 v3, v31, v49
	s_waitcnt lgkmcnt(0)
	v_cvt_pk_bf16_f32 v34, v28, v29
	ds_read2_b32 v[28:29], v48 offset0:206 offset1:239
	v_lshlrev_b32_e32 v6, 12, v3
	s_waitcnt lgkmcnt(0)
	v_cvt_pk_bf16_f32 v35, v28, v29
	ds_read2_b32 v[28:29], v48 offset0:16 offset1:49
	v_lshl_add_u64 v[36:37], v[38:39], 0, v[6:7]
	global_store_dwordx4 v[36:37], v[32:35], off sc0 sc1
	v_or_b32_e32 v3, v31, v50
	v_lshlrev_b32_e32 v6, 12, v3
	s_waitcnt lgkmcnt(0)
	v_cvt_pk_bf16_f32 v32, v28, v29
	ds_read2_b32 v[28:29], v48 offset0:82 offset1:115
	s_waitcnt lgkmcnt(0)
	v_cvt_pk_bf16_f32 v33, v28, v29
	ds_read2_b32 v[28:29], v48 offset0:148 offset1:181
	s_waitcnt lgkmcnt(0)
	v_cvt_pk_bf16_f32 v34, v28, v29
	ds_read2_b32 v[28:29], v48 offset0:214 offset1:247
	s_waitcnt lgkmcnt(0)
	v_cvt_pk_bf16_f32 v35, v28, v29
	ds_read2_b32 v[28:29], v48 offset0:24 offset1:57
	v_lshl_add_u64 v[36:37], v[38:39], 0, v[6:7]
	global_store_dwordx4 v[36:37], v[32:35], off sc0 sc1
	s_waitcnt lgkmcnt(0)
	v_cvt_pk_bf16_f32 v28, v28, v29
	ds_read2_b32 v[32:33], v48 offset0:90 offset1:123
	s_waitcnt lgkmcnt(0)
	v_cvt_pk_bf16_f32 v29, v32, v33
	ds_read2_b32 v[32:33], v48 offset0:156 offset1:189
	v_or_b32_e32 v3, v31, v51
	s_waitcnt lgkmcnt(0)
	v_cvt_pk_bf16_f32 v30, v32, v33
	ds_read2_b32 v[32:33], v48 offset0:222 offset1:255
	v_lshlrev_b32_e32 v6, 12, v3
	s_waitcnt lgkmcnt(0)
	v_cvt_pk_bf16_f32 v31, v32, v33
	v_lshl_add_u64 v[32:33], v[38:39], 0, v[6:7]
	global_store_dwordx4 v[32:33], v[28:31], off sc0 sc1
	s_waitcnt lgkmcnt(0)

.Lmy_lt_98:

	s_lshl_b32 s41, s27, 1
	s_lshl_b32 s40, s26, 1
	v_or_b32_e32 v6, s41, v30
	s_add_i32 s43, s41, 4
	s_add_i32 s42, s40, 4
	s_add_i32 s44, s40, 8
	s_add_i32 s45, s41, 8
	v_lshlrev_b64 v[70:71], 14, v[6:7]
	v_or_b32_e32 v6, s43, v30
	v_mov_b32_e32 v35, v7
	v_mov_b32_e32 v37, v7
	v_mov_b32_e32 v39, v7
	v_or_b32_e32 v34, s40, v3
	s_add_i32 s46, s40, 12
	s_add_i32 s47, s41, 12
	s_add_i32 s48, s40, 16
	s_add_i32 s50, s40, 20
	s_add_i32 s52, s40, 24
	s_add_i32 s54, s40, 28
	v_or_b32_e32 v36, s42, v3
	v_or_b32_e32 v38, s44, v3
	v_lshlrev_b64 v[72:73], 14, v[6:7]
	v_or_b32_e32 v6, s45, v30
	v_mov_b32_e32 v41, v7
	v_mov_b32_e32 v43, v7
	v_mov_b32_e32 v45, v7
	v_mov_b32_e32 v67, v7
	v_mov_b32_e32 v69, v7
	s_add_i32 s49, s41, 16
	v_lshlrev_b64 v[34:35], 14, v[34:35]
	v_or_b32_e32 v40, s46, v3
	v_or_b32_e32 v42, s48, v3
	v_or_b32_e32 v44, s50, v3
	v_or_b32_e32 v66, s52, v3
	v_or_b32_e32 v68, s54, v3
	v_lshl_add_u64 v[70:71], v[28:29], 0, v[70:71]
	v_lshlrev_b64 v[36:37], 14, v[36:37]
	v_lshlrev_b64 v[38:39], 14, v[38:39]
	v_lshlrev_b64 v[74:75], 14, v[6:7]
	v_or_b32_e32 v6, s47, v30
	s_add_i32 s51, s41, 20
	v_lshl_add_u64 v[34:35], v[28:29], 0, v[34:35]
	v_lshlrev_b64 v[40:41], 14, v[40:41]
	v_lshlrev_b64 v[42:43], 14, v[42:43]
	v_lshlrev_b64 v[44:45], 14, v[44:45]
	v_lshlrev_b64 v[66:67], 14, v[66:67]
	v_lshlrev_b64 v[68:69], 14, v[68:69]
	v_lshl_add_u64 v[72:73], v[28:29], 0, v[72:73]
	v_lshl_add_u64 v[36:37], v[28:29], 0, v[36:37]
	v_lshl_add_u64 v[38:39], v[28:29], 0, v[38:39]
	global_load_dword v33, v[70:71], off
	global_load_dword v65, v[34:35], off
	v_lshlrev_b64 v[70:71], 14, v[6:7]
	v_or_b32_e32 v6, s49, v30
	s_add_i32 s53, s41, 24
	v_lshl_add_u64 v[40:41], v[28:29], 0, v[40:41]
	v_lshl_add_u64 v[42:43], v[28:29], 0, v[42:43]
	v_lshl_add_u64 v[44:45], v[28:29], 0, v[44:45]
	v_lshl_add_u64 v[66:67], v[28:29], 0, v[66:67]
	v_lshl_add_u64 v[68:69], v[28:29], 0, v[68:69]
	global_load_dword v86, v[72:73], off
	global_load_dword v87, v[36:37], off
	global_load_dword v88, v[38:39], off
	global_load_dword v89, v[40:41], off
	global_load_dword v90, v[42:43], off
	global_load_dword v91, v[44:45], off
	global_load_dword v92, v[66:67], off
	global_load_dword v93, v[68:69], off
	v_lshl_add_u64 v[36:37], v[28:29], 0, v[70:71]
	v_lshlrev_b64 v[38:39], 14, v[6:7]
	v_or_b32_e32 v6, s51, v30
	s_add_i32 s55, s41, 28
	v_lshl_add_u64 v[34:35], v[28:29], 0, v[74:75]
	global_load_dword v94, v[36:37], off
	global_load_dword v95, v[34:35], off
	v_lshlrev_b64 v[36:37], 14, v[6:7]
	v_or_b32_e32 v6, s53, v30
	v_lshl_add_u64 v[34:35], v[28:29], 0, v[38:39]
	v_lshlrev_b64 v[38:39], 14, v[6:7]
	v_or_b32_e32 v6, s55, v30
	v_lshlrev_b64 v[40:41], 14, v[6:7]
	v_lshl_add_u64 v[40:41], v[28:29], 0, v[40:41]
	v_lshl_add_u64 v[36:37], v[28:29], 0, v[36:37]
	v_lshl_add_u64 v[38:39], v[28:29], 0, v[38:39]
	global_load_dword v6, v[40:41], off
	global_load_dword v96, v[38:39], off
	global_load_dword v97, v[36:37], off
	global_load_dword v98, v[34:35], off
	v_or_b32_e32 v36, s40, v1
	v_or_b32_e32 v34, s41, v2
	s_add_i32 s27, s27, 16
	s_add_i32 s26, s26, 16
	s_add_i32 s39, s39, -16
	v_mad_u64_u32 v[34:35], s[40:41], v34, s25, v[4:5]
	v_mad_u64_u32 v[36:37], s[40:41], v36, s25, v[4:5]
	v_or_b32_e32 v35, s42, v1
	v_or_b32_e32 v37, s43, v2
	v_or_b32_e32 v44, s44, v1
	v_or_b32_e32 v42, s45, v2
	v_or_b32_e32 v68, s46, v1
	v_or_b32_e32 v66, s47, v2
	v_or_b32_e32 v72, s48, v1
	v_or_b32_e32 v70, s49, v2
	v_or_b32_e32 v76, s50, v1
	v_or_b32_e32 v74, s51, v2
	v_or_b32_e32 v80, s52, v1
	v_or_b32_e32 v78, s53, v2
	v_or_b32_e32 v84, s54, v1
	v_or_b32_e32 v82, s55, v2
	s_cmp_lg_u32 s39, 0
	v_mad_u64_u32 v[38:39], s[40:41], v37, s25, v[4:5]
	v_mad_u64_u32 v[40:41], s[40:41], v35, s25, v[4:5]
	v_mad_u64_u32 v[42:43], s[40:41], v42, s25, v[4:5]
	v_mad_u64_u32 v[44:45], s[40:41], v44, s25, v[4:5]
	v_mad_u64_u32 v[66:67], s[40:41], v66, s25, v[4:5]
	v_mad_u64_u32 v[68:69], s[40:41], v68, s25, v[4:5]
	v_mad_u64_u32 v[70:71], s[40:41], v70, s25, v[4:5]
	v_mad_u64_u32 v[72:73], s[40:41], v72, s25, v[4:5]
	v_mad_u64_u32 v[74:75], s[40:41], v74, s25, v[4:5]
	v_mad_u64_u32 v[76:77], s[40:41], v76, s25, v[4:5]
	v_mad_u64_u32 v[78:79], s[40:41], v78, s25, v[4:5]
	v_mad_u64_u32 v[80:81], s[40:41], v80, s25, v[4:5]
	v_mad_u64_u32 v[82:83], s[40:41], v82, s25, v[4:5]
	v_mad_u64_u32 v[84:85], s[40:41], v84, s25, v[4:5]
	s_waitcnt vmcnt(15)
	ds_write_b32 v34, v33
	s_waitcnt vmcnt(14)
	ds_write_b32 v36, v65
	s_waitcnt vmcnt(13)
	ds_write_b32 v38, v86
	s_waitcnt vmcnt(12)
	ds_write_b32 v40, v87
	s_waitcnt vmcnt(4)
	ds_write_b32 v42, v95
	ds_write_b32 v44, v88
	ds_write_b32 v66, v94
	ds_write_b32 v68, v89
	s_waitcnt vmcnt(0)
	ds_write_b32 v70, v98
	ds_write_b32 v72, v90
	ds_write_b32 v74, v97
	ds_write_b32 v76, v91
	ds_write_b32 v78, v96
	ds_write_b32 v80, v92
	ds_write_b32 v82, v6
	ds_write_b32 v84, v93
	s_cbranch_scc1 .Lmy_lt_98

	s_waitcnt lgkmcnt(0)
	ds_read2_b32 v[28:29], v48 offset1:33
	s_waitcnt lgkmcnt(0)
	v_cvt_pk_bf16_f32 v34, v28, v29
	ds_read2_b32 v[28:29], v48 offset0:66 offset1:99
	s_waitcnt lgkmcnt(0)
	v_cvt_pk_bf16_f32 v35, v28, v29
	ds_read2_b32 v[28:29], v48 offset0:132 offset1:165
	v_lshlrev_b32_e32 v6, 1, v32
	v_or_b32_e32 v3, v31, v47
	s_waitcnt lgkmcnt(0)
	v_cvt_pk_bf16_f32 v36, v28, v29
	ds_read2_b32 v[28:29], v48 offset0:198 offset1:231
	v_lshl_add_u64 v[38:39], v[12:13], 0, v[6:7]
	v_lshlrev_b32_e32 v6, 11, v3
	s_waitcnt lgkmcnt(0)
	v_cvt_pk_bf16_f32 v37, v28, v29
	ds_read2_b32 v[28:29], v48 offset0:8 offset1:41
	v_lshl_add_u64 v[32:33], v[38:39], 0, v[6:7]
	global_store_dwordx4 v[32:33], v[34:37], off sc0 sc1
	s_waitcnt lgkmcnt(0)
	v_cvt_pk_bf16_f32 v32, v28, v29
	ds_read2_b32 v[28:29], v48 offset0:74 offset1:107
	s_waitcnt lgkmcnt(0)
	v_cvt_pk_bf16_f32 v33, v28, v29
	ds_read2_b32 v[28:29], v48 offset0:140 offset1:173
	v_or_b32_e32 v3, v31, v49
	s_waitcnt lgkmcnt(0)
	v_cvt_pk_bf16_f32 v34, v28, v29
	ds_read2_b32 v[28:29], v48 offset0:206 offset1:239
	v_lshlrev_b32_e32 v6, 11, v3
	s_waitcnt lgkmcnt(0)
	v_cvt_pk_bf16_f32 v35, v28, v29
	ds_read2_b32 v[28:29], v48 offset0:16 offset1:49
	v_lshl_add_u64 v[36:37], v[38:39], 0, v[6:7]
	global_store_dwordx4 v[36:37], v[32:35], off sc0 sc1
	v_or_b32_e32 v3, v31, v50
	v_lshlrev_b32_e32 v6, 11, v3
	s_waitcnt lgkmcnt(0)
	v_cvt_pk_bf16_f32 v32, v28, v29
	ds_read2_b32 v[28:29], v48 offset0:82 offset1:115
	s_waitcnt lgkmcnt(0)
	v_cvt_pk_bf16_f32 v33, v28, v29
	ds_read2_b32 v[28:29], v48 offset0:148 offset1:181
	s_waitcnt lgkmcnt(0)
	v_cvt_pk_bf16_f32 v34, v28, v29
	ds_read2_b32 v[28:29], v48 offset0:214 offset1:247
	s_waitcnt lgkmcnt(0)
	v_cvt_pk_bf16_f32 v35, v28, v29
	ds_read2_b32 v[28:29], v48 offset0:24 offset1:57
	v_lshl_add_u64 v[36:37], v[38:39], 0, v[6:7]
	global_store_dwordx4 v[36:37], v[32:35], off sc0 sc1
	s_waitcnt lgkmcnt(0)
	v_cvt_pk_bf16_f32 v28, v28, v29
	ds_read2_b32 v[32:33], v48 offset0:90 offset1:123
	s_waitcnt lgkmcnt(0)
	v_cvt_pk_bf16_f32 v29, v32, v33
	ds_read2_b32 v[32:33], v48 offset0:156 offset1:189
	v_or_b32_e32 v3, v31, v51
	s_waitcnt lgkmcnt(0)
	v_cvt_pk_bf16_f32 v30, v32, v33
	ds_read2_b32 v[32:33], v48 offset0:222 offset1:255
	v_lshlrev_b32_e32 v6, 11, v3
	s_waitcnt lgkmcnt(0)
	v_cvt_pk_bf16_f32 v31, v32, v33
	v_lshl_add_u64 v[32:33], v[38:39], 0, v[6:7]
	global_store_dwordx4 v[32:33], v[28:31], off sc0 sc1
	s_waitcnt lgkmcnt(0)

.Lmy_lt_103:

	s_lshl_b32 s39, s23, 1
	s_lshl_b32 s27, s22, 1
	v_or_b32_e32 v6, s39, v30
	s_add_i32 s43, s39, 4
	s_add_i32 s42, s27, 4
	s_add_i32 s44, s27, 8
	s_add_i32 s45, s39, 8
	v_lshlrev_b64 v[70:71], 12, v[6:7]
	v_or_b32_e32 v6, s43, v30
	v_mov_b32_e32 v35, v7
	v_mov_b32_e32 v37, v7
	v_mov_b32_e32 v39, v7
	v_or_b32_e32 v34, s27, v3
	s_add_i32 s46, s27, 12
	s_add_i32 s47, s39, 12
	s_add_i32 s48, s27, 16
	s_add_i32 s50, s27, 20
	s_add_i32 s52, s27, 24
	s_add_i32 s54, s27, 28
	v_or_b32_e32 v36, s42, v3
	v_or_b32_e32 v38, s44, v3
	v_lshlrev_b64 v[72:73], 12, v[6:7]
	v_or_b32_e32 v6, s45, v30
	v_mov_b32_e32 v41, v7
	v_mov_b32_e32 v43, v7
	v_mov_b32_e32 v45, v7
	v_mov_b32_e32 v67, v7
	v_mov_b32_e32 v69, v7
	s_add_i32 s49, s39, 16
	v_lshlrev_b64 v[34:35], 12, v[34:35]
	v_or_b32_e32 v40, s46, v3
	v_or_b32_e32 v42, s48, v3
	v_or_b32_e32 v44, s50, v3
	v_or_b32_e32 v66, s52, v3
	v_or_b32_e32 v68, s54, v3
	v_lshl_add_u64 v[70:71], v[28:29], 0, v[70:71]
	v_lshlrev_b64 v[36:37], 12, v[36:37]
	v_lshlrev_b64 v[38:39], 12, v[38:39]
	v_lshlrev_b64 v[74:75], 12, v[6:7]
	v_or_b32_e32 v6, s47, v30
	s_add_i32 s51, s39, 20
	v_lshl_add_u64 v[34:35], v[28:29], 0, v[34:35]
	v_lshlrev_b64 v[40:41], 12, v[40:41]
	v_lshlrev_b64 v[42:43], 12, v[42:43]
	v_lshlrev_b64 v[44:45], 12, v[44:45]
	v_lshlrev_b64 v[66:67], 12, v[66:67]
	v_lshlrev_b64 v[68:69], 12, v[68:69]
	v_lshl_add_u64 v[72:73], v[28:29], 0, v[72:73]
	v_lshl_add_u64 v[36:37], v[28:29], 0, v[36:37]
	v_lshl_add_u64 v[38:39], v[28:29], 0, v[38:39]
	global_load_dword v33, v[70:71], off
	global_load_dword v65, v[34:35], off
	v_lshlrev_b64 v[70:71], 12, v[6:7]
	v_or_b32_e32 v6, s49, v30
	s_add_i32 s53, s39, 24
	v_lshl_add_u64 v[40:41], v[28:29], 0, v[40:41]
	v_lshl_add_u64 v[42:43], v[28:29], 0, v[42:43]
	v_lshl_add_u64 v[44:45], v[28:29], 0, v[44:45]
	v_lshl_add_u64 v[66:67], v[28:29], 0, v[66:67]
	v_lshl_add_u64 v[68:69], v[28:29], 0, v[68:69]
	global_load_dword v86, v[72:73], off
	global_load_dword v87, v[36:37], off
	global_load_dword v88, v[38:39], off
	global_load_dword v89, v[40:41], off
	global_load_dword v90, v[42:43], off
	global_load_dword v91, v[44:45], off
	global_load_dword v92, v[66:67], off
	global_load_dword v93, v[68:69], off
	v_lshl_add_u64 v[36:37], v[28:29], 0, v[70:71]
	v_lshlrev_b64 v[38:39], 12, v[6:7]
	v_or_b32_e32 v6, s51, v30
	s_add_i32 s55, s39, 28
	v_lshl_add_u64 v[34:35], v[28:29], 0, v[74:75]
	global_load_dword v94, v[36:37], off
	global_load_dword v95, v[34:35], off
	v_lshlrev_b64 v[36:37], 12, v[6:7]
	v_or_b32_e32 v6, s53, v30
	v_lshl_add_u64 v[34:35], v[28:29], 0, v[38:39]
	v_lshlrev_b64 v[38:39], 12, v[6:7]
	v_or_b32_e32 v6, s55, v30
	v_lshlrev_b64 v[40:41], 12, v[6:7]
	v_lshl_add_u64 v[40:41], v[28:29], 0, v[40:41]
	v_lshl_add_u64 v[36:37], v[28:29], 0, v[36:37]
	v_lshl_add_u64 v[38:39], v[28:29], 0, v[38:39]
	global_load_dword v6, v[40:41], off
	global_load_dword v96, v[38:39], off
	global_load_dword v97, v[36:37], off
	global_load_dword v98, v[34:35], off
	v_or_b32_e32 v36, s27, v1
	v_or_b32_e32 v34, s39, v2
	s_add_i32 s23, s23, 16
	s_add_i32 s22, s22, 16
	s_add_i32 s26, s26, -16
	v_mad_u64_u32 v[34:35], s[40:41], v34, s25, v[4:5]
	v_mad_u64_u32 v[36:37], s[40:41], v36, s25, v[4:5]
	v_or_b32_e32 v35, s42, v1
	v_or_b32_e32 v37, s43, v2
	v_or_b32_e32 v44, s44, v1
	v_or_b32_e32 v42, s45, v2
	v_or_b32_e32 v68, s46, v1
	v_or_b32_e32 v66, s47, v2
	v_or_b32_e32 v72, s48, v1
	v_or_b32_e32 v70, s49, v2
	v_or_b32_e32 v76, s50, v1
	v_or_b32_e32 v74, s51, v2
	v_or_b32_e32 v80, s52, v1
	v_or_b32_e32 v78, s53, v2
	v_or_b32_e32 v84, s54, v1
	v_or_b32_e32 v82, s55, v2
	s_cmp_lg_u32 s26, 0
	v_mad_u64_u32 v[38:39], s[40:41], v37, s25, v[4:5]
	v_mad_u64_u32 v[40:41], s[40:41], v35, s25, v[4:5]
	v_mad_u64_u32 v[42:43], s[40:41], v42, s25, v[4:5]
	v_mad_u64_u32 v[44:45], s[40:41], v44, s25, v[4:5]
	v_mad_u64_u32 v[66:67], s[40:41], v66, s25, v[4:5]
	v_mad_u64_u32 v[68:69], s[40:41], v68, s25, v[4:5]
	v_mad_u64_u32 v[70:71], s[40:41], v70, s25, v[4:5]
	v_mad_u64_u32 v[72:73], s[40:41], v72, s25, v[4:5]
	v_mad_u64_u32 v[74:75], s[40:41], v74, s25, v[4:5]
	v_mad_u64_u32 v[76:77], s[40:41], v76, s25, v[4:5]
	v_mad_u64_u32 v[78:79], s[40:41], v78, s25, v[4:5]
	v_mad_u64_u32 v[80:81], s[40:41], v80, s25, v[4:5]
	v_mad_u64_u32 v[82:83], s[40:41], v82, s25, v[4:5]
	v_mad_u64_u32 v[84:85], s[40:41], v84, s25, v[4:5]
	s_waitcnt vmcnt(15)
	ds_write_b32 v34, v33
	s_waitcnt vmcnt(14)
	ds_write_b32 v36, v65
	s_waitcnt vmcnt(13)
	ds_write_b32 v38, v86
	s_waitcnt vmcnt(12)
	ds_write_b32 v40, v87
	s_waitcnt vmcnt(4)
	ds_write_b32 v42, v95
	ds_write_b32 v44, v88
	ds_write_b32 v66, v94
	ds_write_b32 v68, v89
	s_waitcnt vmcnt(0)
	ds_write_b32 v70, v98
	ds_write_b32 v72, v90
	ds_write_b32 v74, v97
	ds_write_b32 v76, v91
	ds_write_b32 v78, v96
	ds_write_b32 v80, v92
	ds_write_b32 v82, v6
	ds_write_b32 v84, v93
	s_cbranch_scc1 .Lmy_lt_103

	s_waitcnt lgkmcnt(0)
	ds_read2_b32 v[28:29], v48 offset1:33
	s_waitcnt lgkmcnt(0)
	v_cvt_pk_bf16_f32 v34, v28, v29
	ds_read2_b32 v[28:29], v48 offset0:66 offset1:99
	s_waitcnt lgkmcnt(0)
	v_cvt_pk_bf16_f32 v35, v28, v29
	ds_read2_b32 v[28:29], v48 offset0:132 offset1:165
	v_lshlrev_b32_e32 v6, 1, v32
	v_or_b32_e32 v3, v31, v47
	s_waitcnt lgkmcnt(0)
	v_cvt_pk_bf16_f32 v36, v28, v29
	ds_read2_b32 v[28:29], v48 offset0:198 offset1:231
	v_lshl_add_u64 v[38:39], v[14:15], 0, v[6:7]
	v_lshlrev_b32_e32 v6, 11, v3
	s_waitcnt lgkmcnt(0)
	v_cvt_pk_bf16_f32 v37, v28, v29
	ds_read2_b32 v[28:29], v48 offset0:8 offset1:41
	v_lshl_add_u64 v[32:33], v[38:39], 0, v[6:7]
	global_store_dwordx4 v[32:33], v[34:37], off sc0 sc1
	s_waitcnt lgkmcnt(0)
	v_cvt_pk_bf16_f32 v32, v28, v29
	ds_read2_b32 v[28:29], v48 offset0:74 offset1:107
	s_waitcnt lgkmcnt(0)
	v_cvt_pk_bf16_f32 v33, v28, v29
	ds_read2_b32 v[28:29], v48 offset0:140 offset1:173
	v_or_b32_e32 v3, v31, v49
	s_waitcnt lgkmcnt(0)
	v_cvt_pk_bf16_f32 v34, v28, v29
	ds_read2_b32 v[28:29], v48 offset0:206 offset1:239
	v_lshlrev_b32_e32 v6, 11, v3
	s_waitcnt lgkmcnt(0)
	v_cvt_pk_bf16_f32 v35, v28, v29
	ds_read2_b32 v[28:29], v48 offset0:16 offset1:49
	v_lshl_add_u64 v[36:37], v[38:39], 0, v[6:7]
	global_store_dwordx4 v[36:37], v[32:35], off sc0 sc1
	v_or_b32_e32 v3, v31, v50
	v_lshlrev_b32_e32 v6, 11, v3
	s_waitcnt lgkmcnt(0)
	v_cvt_pk_bf16_f32 v32, v28, v29
	ds_read2_b32 v[28:29], v48 offset0:82 offset1:115
	s_waitcnt lgkmcnt(0)
	v_cvt_pk_bf16_f32 v33, v28, v29
	ds_read2_b32 v[28:29], v48 offset0:148 offset1:181
	s_waitcnt lgkmcnt(0)
	v_cvt_pk_bf16_f32 v34, v28, v29
	ds_read2_b32 v[28:29], v48 offset0:214 offset1:247
	s_waitcnt lgkmcnt(0)
	v_cvt_pk_bf16_f32 v35, v28, v29
	ds_read2_b32 v[28:29], v48 offset0:24 offset1:57
	v_lshl_add_u64 v[36:37], v[38:39], 0, v[6:7]
	global_store_dwordx4 v[36:37], v[32:35], off sc0 sc1
	s_waitcnt lgkmcnt(0)
	v_cvt_pk_bf16_f32 v28, v28, v29
	ds_read2_b32 v[32:33], v48 offset0:90 offset1:123
	s_waitcnt lgkmcnt(0)
	v_cvt_pk_bf16_f32 v29, v32, v33
	ds_read2_b32 v[32:33], v48 offset0:156 offset1:189
	v_or_b32_e32 v3, v31, v51
	s_waitcnt lgkmcnt(0)
	v_cvt_pk_bf16_f32 v30, v32, v33
	ds_read2_b32 v[32:33], v48 offset0:222 offset1:255
	v_lshlrev_b32_e32 v6, 11, v3
	s_waitcnt lgkmcnt(0)
	v_cvt_pk_bf16_f32 v31, v32, v33
	v_lshl_add_u64 v[32:33], v[38:39], 0, v[6:7]
	global_store_dwordx4 v[32:33], v[28:31], off sc0 sc1
	s_waitcnt lgkmcnt(0)

.Lmy_lt_108:

	s_lshl_b32 s26, s21, 1
	s_lshl_b32 s23, s20, 1
	v_or_b32_e32 v6, s26, v30
	s_add_i32 s40, s26, 4
	s_add_i32 s39, s23, 4
	s_add_i32 s41, s23, 8
	s_add_i32 s42, s26, 8
	v_lshlrev_b64 v[70:71], 12, v[6:7]
	v_or_b32_e32 v6, s40, v30
	v_mov_b32_e32 v35, v7
	v_mov_b32_e32 v37, v7
	v_mov_b32_e32 v39, v7
	v_or_b32_e32 v34, s23, v3
	s_add_i32 s43, s23, 12
	s_add_i32 s44, s26, 12
	s_add_i32 s45, s23, 16
	s_add_i32 s47, s23, 20
	s_add_i32 s49, s23, 24
	s_add_i32 s51, s23, 28
	v_or_b32_e32 v36, s39, v3
	v_or_b32_e32 v38, s41, v3
	v_lshlrev_b64 v[72:73], 12, v[6:7]
	v_or_b32_e32 v6, s42, v30
	v_mov_b32_e32 v41, v7
	v_mov_b32_e32 v43, v7
	v_mov_b32_e32 v45, v7
	v_mov_b32_e32 v67, v7
	v_mov_b32_e32 v69, v7
	s_add_i32 s46, s26, 16
	v_lshlrev_b64 v[34:35], 12, v[34:35]
	v_or_b32_e32 v40, s43, v3
	v_or_b32_e32 v42, s45, v3
	v_or_b32_e32 v44, s47, v3
	v_or_b32_e32 v66, s49, v3
	v_or_b32_e32 v68, s51, v3
	v_lshl_add_u64 v[70:71], v[28:29], 0, v[70:71]
	v_lshlrev_b64 v[36:37], 12, v[36:37]
	v_lshlrev_b64 v[38:39], 12, v[38:39]
	v_lshlrev_b64 v[74:75], 12, v[6:7]
	v_or_b32_e32 v6, s44, v30
	s_add_i32 s48, s26, 20
	v_lshl_add_u64 v[34:35], v[28:29], 0, v[34:35]
	v_lshlrev_b64 v[40:41], 12, v[40:41]
	v_lshlrev_b64 v[42:43], 12, v[42:43]
	v_lshlrev_b64 v[44:45], 12, v[44:45]
	v_lshlrev_b64 v[66:67], 12, v[66:67]
	v_lshlrev_b64 v[68:69], 12, v[68:69]
	v_lshl_add_u64 v[72:73], v[28:29], 0, v[72:73]
	v_lshl_add_u64 v[36:37], v[28:29], 0, v[36:37]
	v_lshl_add_u64 v[38:39], v[28:29], 0, v[38:39]
	global_load_dword v33, v[70:71], off
	global_load_dword v65, v[34:35], off
	v_lshlrev_b64 v[70:71], 12, v[6:7]
	v_or_b32_e32 v6, s46, v30
	s_add_i32 s50, s26, 24
	v_lshl_add_u64 v[40:41], v[28:29], 0, v[40:41]
	v_lshl_add_u64 v[42:43], v[28:29], 0, v[42:43]
	v_lshl_add_u64 v[44:45], v[28:29], 0, v[44:45]
	v_lshl_add_u64 v[66:67], v[28:29], 0, v[66:67]
	v_lshl_add_u64 v[68:69], v[28:29], 0, v[68:69]
	global_load_dword v86, v[72:73], off
	global_load_dword v87, v[36:37], off
	global_load_dword v88, v[38:39], off
	global_load_dword v89, v[40:41], off
	global_load_dword v90, v[42:43], off
	global_load_dword v91, v[44:45], off
	global_load_dword v92, v[66:67], off
	global_load_dword v93, v[68:69], off
	v_lshl_add_u64 v[36:37], v[28:29], 0, v[70:71]
	v_lshlrev_b64 v[38:39], 12, v[6:7]
	v_or_b32_e32 v6, s48, v30
	s_add_i32 s52, s26, 28
	v_lshl_add_u64 v[34:35], v[28:29], 0, v[74:75]
	global_load_dword v94, v[36:37], off
	global_load_dword v95, v[34:35], off
	v_lshlrev_b64 v[36:37], 12, v[6:7]
	v_or_b32_e32 v6, s50, v30
	v_lshl_add_u64 v[34:35], v[28:29], 0, v[38:39]
	v_lshlrev_b64 v[38:39], 12, v[6:7]
	v_or_b32_e32 v6, s52, v30
	v_lshlrev_b64 v[40:41], 12, v[6:7]
	v_lshl_add_u64 v[40:41], v[28:29], 0, v[40:41]
	v_lshl_add_u64 v[36:37], v[28:29], 0, v[36:37]
	v_lshl_add_u64 v[38:39], v[28:29], 0, v[38:39]
	global_load_dword v6, v[40:41], off
	global_load_dword v96, v[38:39], off
	global_load_dword v97, v[36:37], off
	global_load_dword v98, v[34:35], off
	v_or_b32_e32 v36, s23, v1
	v_or_b32_e32 v34, s26, v2
	s_add_i32 s21, s21, 16
	s_add_i32 s20, s20, 16
	s_add_i32 s22, s22, -16
	v_mad_u64_u32 v[34:35], s[26:27], v34, s25, v[4:5]
	v_mad_u64_u32 v[36:37], s[26:27], v36, s25, v[4:5]
	v_or_b32_e32 v35, s39, v1
	v_or_b32_e32 v37, s40, v2
	v_or_b32_e32 v44, s41, v1
	v_or_b32_e32 v42, s42, v2
	v_or_b32_e32 v68, s43, v1
	v_or_b32_e32 v66, s44, v2
	v_or_b32_e32 v72, s45, v1
	v_or_b32_e32 v70, s46, v2
	v_or_b32_e32 v76, s47, v1
	v_or_b32_e32 v74, s48, v2
	v_or_b32_e32 v80, s49, v1
	v_or_b32_e32 v78, s50, v2
	v_or_b32_e32 v84, s51, v1
	v_or_b32_e32 v82, s52, v2
	s_cmp_lg_u32 s22, 0
	v_mad_u64_u32 v[38:39], s[26:27], v37, s25, v[4:5]
	v_mad_u64_u32 v[40:41], s[26:27], v35, s25, v[4:5]
	v_mad_u64_u32 v[42:43], s[26:27], v42, s25, v[4:5]
	v_mad_u64_u32 v[44:45], s[26:27], v44, s25, v[4:5]
	v_mad_u64_u32 v[66:67], s[26:27], v66, s25, v[4:5]
	v_mad_u64_u32 v[68:69], s[26:27], v68, s25, v[4:5]
	v_mad_u64_u32 v[70:71], s[26:27], v70, s25, v[4:5]
	v_mad_u64_u32 v[72:73], s[26:27], v72, s25, v[4:5]
	v_mad_u64_u32 v[74:75], s[26:27], v74, s25, v[4:5]
	v_mad_u64_u32 v[76:77], s[26:27], v76, s25, v[4:5]
	v_mad_u64_u32 v[78:79], s[26:27], v78, s25, v[4:5]
	v_mad_u64_u32 v[80:81], s[26:27], v80, s25, v[4:5]
	v_mad_u64_u32 v[82:83], s[26:27], v82, s25, v[4:5]
	v_mad_u64_u32 v[84:85], s[26:27], v84, s25, v[4:5]
	s_waitcnt vmcnt(15)
	ds_write_b32 v34, v33
	s_waitcnt vmcnt(14)
	ds_write_b32 v36, v65
	s_waitcnt vmcnt(13)
	ds_write_b32 v38, v86
	s_waitcnt vmcnt(12)
	ds_write_b32 v40, v87
	s_waitcnt vmcnt(4)
	ds_write_b32 v42, v95
	ds_write_b32 v44, v88
	ds_write_b32 v66, v94
	ds_write_b32 v68, v89
	s_waitcnt vmcnt(0)
	ds_write_b32 v70, v98
	ds_write_b32 v72, v90
	ds_write_b32 v74, v97
	ds_write_b32 v76, v91
	ds_write_b32 v78, v96
	ds_write_b32 v80, v92
	ds_write_b32 v82, v6
	ds_write_b32 v84, v93
	s_cbranch_scc1 .Lmy_lt_108

	s_waitcnt lgkmcnt(0)
	ds_read2_b32 v[28:29], v48 offset1:33
	s_waitcnt lgkmcnt(0)
	v_cvt_pk_bf16_f32 v34, v28, v29
	ds_read2_b32 v[28:29], v48 offset0:66 offset1:99
	s_waitcnt lgkmcnt(0)
	v_cvt_pk_bf16_f32 v35, v28, v29
	ds_read2_b32 v[28:29], v48 offset0:132 offset1:165
	v_lshlrev_b32_e32 v6, 1, v32
	v_or_b32_e32 v3, v31, v47
	s_waitcnt lgkmcnt(0)
	v_cvt_pk_bf16_f32 v36, v28, v29
	ds_read2_b32 v[28:29], v48 offset0:198 offset1:231
	v_lshl_add_u64 v[38:39], v[16:17], 0, v[6:7]
	v_lshlrev_b32_e32 v6, 10, v3
	s_waitcnt lgkmcnt(0)
	v_cvt_pk_bf16_f32 v37, v28, v29
	ds_read2_b32 v[28:29], v48 offset0:8 offset1:41
	v_lshl_add_u64 v[32:33], v[38:39], 0, v[6:7]
	global_store_dwordx4 v[32:33], v[34:37], off sc0 sc1
	s_waitcnt lgkmcnt(0)
	v_cvt_pk_bf16_f32 v32, v28, v29
	ds_read2_b32 v[28:29], v48 offset0:74 offset1:107
	s_waitcnt lgkmcnt(0)
	v_cvt_pk_bf16_f32 v33, v28, v29
	ds_read2_b32 v[28:29], v48 offset0:140 offset1:173
	v_or_b32_e32 v3, v31, v49
	s_waitcnt lgkmcnt(0)
	v_cvt_pk_bf16_f32 v34, v28, v29
	ds_read2_b32 v[28:29], v48 offset0:206 offset1:239
	v_lshlrev_b32_e32 v6, 10, v3
	s_waitcnt lgkmcnt(0)
	v_cvt_pk_bf16_f32 v35, v28, v29
	ds_read2_b32 v[28:29], v48 offset0:16 offset1:49
	v_lshl_add_u64 v[36:37], v[38:39], 0, v[6:7]
	global_store_dwordx4 v[36:37], v[32:35], off sc0 sc1
	v_or_b32_e32 v3, v31, v50
	v_lshlrev_b32_e32 v6, 10, v3
	s_waitcnt lgkmcnt(0)
	v_cvt_pk_bf16_f32 v32, v28, v29
	ds_read2_b32 v[28:29], v48 offset0:82 offset1:115
	s_waitcnt lgkmcnt(0)
	v_cvt_pk_bf16_f32 v33, v28, v29
	ds_read2_b32 v[28:29], v48 offset0:148 offset1:181
	s_waitcnt lgkmcnt(0)
	v_cvt_pk_bf16_f32 v34, v28, v29
	ds_read2_b32 v[28:29], v48 offset0:214 offset1:247
	s_waitcnt lgkmcnt(0)
	v_cvt_pk_bf16_f32 v35, v28, v29
	ds_read2_b32 v[28:29], v48 offset0:24 offset1:57
	v_lshl_add_u64 v[36:37], v[38:39], 0, v[6:7]
	global_store_dwordx4 v[36:37], v[32:35], off sc0 sc1
	s_waitcnt lgkmcnt(0)
	v_cvt_pk_bf16_f32 v28, v28, v29
	ds_read2_b32 v[32:33], v48 offset0:90 offset1:123
	s_waitcnt lgkmcnt(0)
	v_cvt_pk_bf16_f32 v29, v32, v33
	ds_read2_b32 v[32:33], v48 offset0:156 offset1:189
	v_or_b32_e32 v3, v31, v51
	s_waitcnt lgkmcnt(0)
	v_cvt_pk_bf16_f32 v30, v32, v33
	ds_read2_b32 v[32:33], v48 offset0:222 offset1:255
	v_lshlrev_b32_e32 v6, 10, v3
	s_waitcnt lgkmcnt(0)
	v_cvt_pk_bf16_f32 v31, v32, v33
	v_lshl_add_u64 v[32:33], v[38:39], 0, v[6:7]
	global_store_dwordx4 v[32:33], v[28:31], off sc0 sc1
	s_waitcnt lgkmcnt(0)

.Lmy_lt_113:

	s_lshl_b32 s22, s19, 1
	s_lshl_b32 s21, s18, 1
	v_or_b32_e32 v6, s22, v30
	s_add_i32 s27, s22, 4
	s_add_i32 s26, s21, 4
	s_add_i32 s39, s21, 8
	s_add_i32 s40, s22, 8
	v_lshlrev_b64 v[70:71], 12, v[6:7]
	v_or_b32_e32 v6, s27, v30
	v_mov_b32_e32 v35, v7
	v_mov_b32_e32 v37, v7
	v_mov_b32_e32 v39, v7
	v_or_b32_e32 v34, s21, v3
	s_add_i32 s41, s21, 12
	s_add_i32 s42, s22, 12
	s_add_i32 s43, s21, 16
	s_add_i32 s45, s21, 20
	s_add_i32 s47, s21, 24
	s_add_i32 s49, s21, 28
	v_or_b32_e32 v36, s26, v3
	v_or_b32_e32 v38, s39, v3
	v_lshlrev_b64 v[72:73], 12, v[6:7]
	v_or_b32_e32 v6, s40, v30
	v_mov_b32_e32 v41, v7
	v_mov_b32_e32 v43, v7
	v_mov_b32_e32 v45, v7
	v_mov_b32_e32 v67, v7
	v_mov_b32_e32 v69, v7
	s_add_i32 s44, s22, 16
	v_lshlrev_b64 v[34:35], 12, v[34:35]
	v_or_b32_e32 v40, s41, v3
	v_or_b32_e32 v42, s43, v3
	v_or_b32_e32 v44, s45, v3
	v_or_b32_e32 v66, s47, v3
	v_or_b32_e32 v68, s49, v3
	v_lshl_add_u64 v[70:71], v[28:29], 0, v[70:71]
	v_lshlrev_b64 v[36:37], 12, v[36:37]
	v_lshlrev_b64 v[38:39], 12, v[38:39]
	v_lshlrev_b64 v[74:75], 12, v[6:7]
	v_or_b32_e32 v6, s42, v30
	s_add_i32 s46, s22, 20
	v_lshl_add_u64 v[34:35], v[28:29], 0, v[34:35]
	v_lshlrev_b64 v[40:41], 12, v[40:41]
	v_lshlrev_b64 v[42:43], 12, v[42:43]
	v_lshlrev_b64 v[44:45], 12, v[44:45]
	v_lshlrev_b64 v[66:67], 12, v[66:67]
	v_lshlrev_b64 v[68:69], 12, v[68:69]
	v_lshl_add_u64 v[72:73], v[28:29], 0, v[72:73]
	v_lshl_add_u64 v[36:37], v[28:29], 0, v[36:37]
	v_lshl_add_u64 v[38:39], v[28:29], 0, v[38:39]
	global_load_dword v33, v[70:71], off
	global_load_dword v65, v[34:35], off
	v_lshlrev_b64 v[70:71], 12, v[6:7]
	v_or_b32_e32 v6, s44, v30
	s_add_i32 s48, s22, 24
	v_lshl_add_u64 v[40:41], v[28:29], 0, v[40:41]
	v_lshl_add_u64 v[42:43], v[28:29], 0, v[42:43]
	v_lshl_add_u64 v[44:45], v[28:29], 0, v[44:45]
	v_lshl_add_u64 v[66:67], v[28:29], 0, v[66:67]
	v_lshl_add_u64 v[68:69], v[28:29], 0, v[68:69]
	global_load_dword v86, v[72:73], off
	global_load_dword v87, v[36:37], off
	global_load_dword v88, v[38:39], off
	global_load_dword v89, v[40:41], off
	global_load_dword v90, v[42:43], off
	global_load_dword v91, v[44:45], off
	global_load_dword v92, v[66:67], off
	global_load_dword v93, v[68:69], off
	v_lshl_add_u64 v[36:37], v[28:29], 0, v[70:71]
	v_lshlrev_b64 v[38:39], 12, v[6:7]
	v_or_b32_e32 v6, s46, v30
	s_add_i32 s50, s22, 28
	v_lshl_add_u64 v[34:35], v[28:29], 0, v[74:75]
	global_load_dword v94, v[36:37], off
	global_load_dword v95, v[34:35], off
	v_lshlrev_b64 v[36:37], 12, v[6:7]
	v_or_b32_e32 v6, s48, v30
	v_lshl_add_u64 v[34:35], v[28:29], 0, v[38:39]
	v_lshlrev_b64 v[38:39], 12, v[6:7]
	v_or_b32_e32 v6, s50, v30
	v_lshlrev_b64 v[40:41], 12, v[6:7]
	v_lshl_add_u64 v[40:41], v[28:29], 0, v[40:41]
	v_lshl_add_u64 v[36:37], v[28:29], 0, v[36:37]
	v_lshl_add_u64 v[38:39], v[28:29], 0, v[38:39]
	global_load_dword v6, v[40:41], off
	global_load_dword v96, v[38:39], off
	global_load_dword v97, v[36:37], off
	global_load_dword v98, v[34:35], off
	v_or_b32_e32 v36, s21, v1
	v_or_b32_e32 v34, s22, v2
	s_add_i32 s19, s19, 16
	s_add_i32 s18, s18, 16
	s_add_i32 s20, s20, -16
	v_mad_u64_u32 v[34:35], s[22:23], v34, s25, v[4:5]
	v_mad_u64_u32 v[36:37], s[22:23], v36, s25, v[4:5]
	v_or_b32_e32 v35, s26, v1
	v_or_b32_e32 v37, s27, v2
	v_or_b32_e32 v44, s39, v1
	v_or_b32_e32 v42, s40, v2
	v_or_b32_e32 v68, s41, v1
	v_or_b32_e32 v66, s42, v2
	v_or_b32_e32 v72, s43, v1
	v_or_b32_e32 v70, s44, v2
	v_or_b32_e32 v76, s45, v1
	v_or_b32_e32 v74, s46, v2
	v_or_b32_e32 v80, s47, v1
	v_or_b32_e32 v78, s48, v2
	v_or_b32_e32 v84, s49, v1
	v_or_b32_e32 v82, s50, v2
	s_cmp_lg_u32 s20, 0
	v_mad_u64_u32 v[38:39], s[22:23], v37, s25, v[4:5]
	v_mad_u64_u32 v[40:41], s[22:23], v35, s25, v[4:5]
	v_mad_u64_u32 v[42:43], s[22:23], v42, s25, v[4:5]
	v_mad_u64_u32 v[44:45], s[22:23], v44, s25, v[4:5]
	v_mad_u64_u32 v[66:67], s[22:23], v66, s25, v[4:5]
	v_mad_u64_u32 v[68:69], s[22:23], v68, s25, v[4:5]
	v_mad_u64_u32 v[70:71], s[22:23], v70, s25, v[4:5]
	v_mad_u64_u32 v[72:73], s[22:23], v72, s25, v[4:5]
	v_mad_u64_u32 v[74:75], s[22:23], v74, s25, v[4:5]
	v_mad_u64_u32 v[76:77], s[22:23], v76, s25, v[4:5]
	v_mad_u64_u32 v[78:79], s[22:23], v78, s25, v[4:5]
	v_mad_u64_u32 v[80:81], s[22:23], v80, s25, v[4:5]
	v_mad_u64_u32 v[82:83], s[22:23], v82, s25, v[4:5]
	v_mad_u64_u32 v[84:85], s[22:23], v84, s25, v[4:5]
	s_waitcnt vmcnt(15)
	ds_write_b32 v34, v33
	s_waitcnt vmcnt(14)
	ds_write_b32 v36, v65
	s_waitcnt vmcnt(13)
	ds_write_b32 v38, v86
	s_waitcnt vmcnt(12)
	ds_write_b32 v40, v87
	s_waitcnt vmcnt(4)
	ds_write_b32 v42, v95
	ds_write_b32 v44, v88
	ds_write_b32 v66, v94
	ds_write_b32 v68, v89
	s_waitcnt vmcnt(0)
	ds_write_b32 v70, v98
	ds_write_b32 v72, v90
	ds_write_b32 v74, v97
	ds_write_b32 v76, v91
	ds_write_b32 v78, v96
	ds_write_b32 v80, v92
	ds_write_b32 v82, v6
	ds_write_b32 v84, v93
	s_cbranch_scc1 .Lmy_lt_113

	s_waitcnt lgkmcnt(0)
	ds_read2_b32 v[28:29], v48 offset1:33
	s_waitcnt lgkmcnt(0)
	v_cvt_pk_bf16_f32 v34, v28, v29
	ds_read2_b32 v[28:29], v48 offset0:66 offset1:99
	s_waitcnt lgkmcnt(0)
	v_cvt_pk_bf16_f32 v35, v28, v29
	ds_read2_b32 v[28:29], v48 offset0:132 offset1:165
	v_lshlrev_b32_e32 v6, 1, v32
	v_or_b32_e32 v3, v31, v47
	s_waitcnt lgkmcnt(0)
	v_cvt_pk_bf16_f32 v36, v28, v29
	ds_read2_b32 v[28:29], v48 offset0:198 offset1:231
	v_lshl_add_u64 v[38:39], v[18:19], 0, v[6:7]
	v_lshlrev_b32_e32 v6, 10, v3
	s_waitcnt lgkmcnt(0)
	v_cvt_pk_bf16_f32 v37, v28, v29
	ds_read2_b32 v[28:29], v48 offset0:8 offset1:41
	v_lshl_add_u64 v[32:33], v[38:39], 0, v[6:7]
	global_store_dwordx4 v[32:33], v[34:37], off sc0 sc1
	s_waitcnt lgkmcnt(0)
	v_cvt_pk_bf16_f32 v32, v28, v29
	ds_read2_b32 v[28:29], v48 offset0:74 offset1:107
	s_waitcnt lgkmcnt(0)
	v_cvt_pk_bf16_f32 v33, v28, v29
	ds_read2_b32 v[28:29], v48 offset0:140 offset1:173
	v_or_b32_e32 v3, v31, v49
	s_waitcnt lgkmcnt(0)
	v_cvt_pk_bf16_f32 v34, v28, v29
	ds_read2_b32 v[28:29], v48 offset0:206 offset1:239
	v_lshlrev_b32_e32 v6, 10, v3
	s_waitcnt lgkmcnt(0)
	v_cvt_pk_bf16_f32 v35, v28, v29
	ds_read2_b32 v[28:29], v48 offset0:16 offset1:49
	v_lshl_add_u64 v[36:37], v[38:39], 0, v[6:7]
	global_store_dwordx4 v[36:37], v[32:35], off sc0 sc1
	v_or_b32_e32 v3, v31, v50
	v_lshlrev_b32_e32 v6, 10, v3
	s_waitcnt lgkmcnt(0)
	v_cvt_pk_bf16_f32 v32, v28, v29
	ds_read2_b32 v[28:29], v48 offset0:82 offset1:115
	s_waitcnt lgkmcnt(0)
	v_cvt_pk_bf16_f32 v33, v28, v29
	ds_read2_b32 v[28:29], v48 offset0:148 offset1:181
	s_waitcnt lgkmcnt(0)
	v_cvt_pk_bf16_f32 v34, v28, v29
	ds_read2_b32 v[28:29], v48 offset0:214 offset1:247
	s_waitcnt lgkmcnt(0)
	v_cvt_pk_bf16_f32 v35, v28, v29
	ds_read2_b32 v[28:29], v48 offset0:24 offset1:57
	v_lshl_add_u64 v[36:37], v[38:39], 0, v[6:7]
	global_store_dwordx4 v[36:37], v[32:35], off sc0 sc1
	s_waitcnt lgkmcnt(0)
	v_cvt_pk_bf16_f32 v28, v28, v29
	ds_read2_b32 v[32:33], v48 offset0:90 offset1:123
	s_waitcnt lgkmcnt(0)
	v_cvt_pk_bf16_f32 v29, v32, v33
	ds_read2_b32 v[32:33], v48 offset0:156 offset1:189
	v_or_b32_e32 v3, v31, v51
	s_waitcnt lgkmcnt(0)
	v_cvt_pk_bf16_f32 v30, v32, v33
	ds_read2_b32 v[32:33], v48 offset0:222 offset1:255
	v_lshlrev_b32_e32 v6, 10, v3
	s_waitcnt lgkmcnt(0)
	v_cvt_pk_bf16_f32 v31, v32, v33
	v_lshl_add_u64 v[32:33], v[38:39], 0, v[6:7]
	global_store_dwordx4 v[32:33], v[28:31], off sc0 sc1
	s_waitcnt lgkmcnt(0)

.Lmy_lt_118:

	s_lshl_b32 s20, s18, 1
	s_lshl_b32 s19, s17, 1
	v_or_b32_e32 v6, s20, v30
	s_add_i32 s23, s20, 4
	s_add_i32 s22, s19, 4
	s_add_i32 s26, s19, 8
	s_add_i32 s27, s20, 8
	v_lshlrev_b64 v[70:71], 12, v[6:7]
	v_or_b32_e32 v6, s23, v30
	v_mov_b32_e32 v35, v7
	v_mov_b32_e32 v37, v7
	v_mov_b32_e32 v39, v7
	v_or_b32_e32 v34, s19, v3
	s_add_i32 s39, s19, 12
	s_add_i32 s40, s20, 12
	s_add_i32 s41, s19, 16
	s_add_i32 s43, s19, 20
	s_add_i32 s45, s19, 24
	s_add_i32 s47, s19, 28
	v_or_b32_e32 v36, s22, v3
	v_or_b32_e32 v38, s26, v3
	v_lshlrev_b64 v[72:73], 12, v[6:7]
	v_or_b32_e32 v6, s27, v30
	v_mov_b32_e32 v41, v7
	v_mov_b32_e32 v43, v7
	v_mov_b32_e32 v45, v7
	v_mov_b32_e32 v67, v7
	v_mov_b32_e32 v69, v7
	s_add_i32 s42, s20, 16
	v_lshlrev_b64 v[34:35], 12, v[34:35]
	v_or_b32_e32 v40, s39, v3
	v_or_b32_e32 v42, s41, v3
	v_or_b32_e32 v44, s43, v3
	v_or_b32_e32 v66, s45, v3
	v_or_b32_e32 v68, s47, v3
	v_lshl_add_u64 v[70:71], v[28:29], 0, v[70:71]
	v_lshlrev_b64 v[36:37], 12, v[36:37]
	v_lshlrev_b64 v[38:39], 12, v[38:39]
	v_lshlrev_b64 v[74:75], 12, v[6:7]
	v_or_b32_e32 v6, s40, v30
	s_add_i32 s44, s20, 20
	v_lshl_add_u64 v[34:35], v[28:29], 0, v[34:35]
	v_lshlrev_b64 v[40:41], 12, v[40:41]
	v_lshlrev_b64 v[42:43], 12, v[42:43]
	v_lshlrev_b64 v[44:45], 12, v[44:45]
	v_lshlrev_b64 v[66:67], 12, v[66:67]
	v_lshlrev_b64 v[68:69], 12, v[68:69]
	v_lshl_add_u64 v[72:73], v[28:29], 0, v[72:73]
	v_lshl_add_u64 v[36:37], v[28:29], 0, v[36:37]
	v_lshl_add_u64 v[38:39], v[28:29], 0, v[38:39]
	global_load_dword v33, v[70:71], off
	global_load_dword v65, v[34:35], off
	v_lshlrev_b64 v[70:71], 12, v[6:7]
	v_or_b32_e32 v6, s42, v30
	s_add_i32 s46, s20, 24
	v_lshl_add_u64 v[40:41], v[28:29], 0, v[40:41]
	v_lshl_add_u64 v[42:43], v[28:29], 0, v[42:43]
	v_lshl_add_u64 v[44:45], v[28:29], 0, v[44:45]
	v_lshl_add_u64 v[66:67], v[28:29], 0, v[66:67]
	v_lshl_add_u64 v[68:69], v[28:29], 0, v[68:69]
	global_load_dword v86, v[72:73], off
	global_load_dword v87, v[36:37], off
	global_load_dword v88, v[38:39], off
	global_load_dword v89, v[40:41], off
	global_load_dword v90, v[42:43], off
	global_load_dword v91, v[44:45], off
	global_load_dword v92, v[66:67], off
	global_load_dword v93, v[68:69], off
	v_lshl_add_u64 v[36:37], v[28:29], 0, v[70:71]
	v_lshlrev_b64 v[38:39], 12, v[6:7]
	v_or_b32_e32 v6, s44, v30
	s_add_i32 s48, s20, 28
	v_lshl_add_u64 v[34:35], v[28:29], 0, v[74:75]
	global_load_dword v94, v[36:37], off
	global_load_dword v95, v[34:35], off
	v_lshlrev_b64 v[36:37], 12, v[6:7]
	v_or_b32_e32 v6, s46, v30
	v_lshl_add_u64 v[34:35], v[28:29], 0, v[38:39]
	v_lshlrev_b64 v[38:39], 12, v[6:7]
	v_or_b32_e32 v6, s48, v30
	v_lshlrev_b64 v[40:41], 12, v[6:7]
	v_lshl_add_u64 v[40:41], v[28:29], 0, v[40:41]
	v_lshl_add_u64 v[36:37], v[28:29], 0, v[36:37]
	v_lshl_add_u64 v[38:39], v[28:29], 0, v[38:39]
	global_load_dword v6, v[40:41], off
	global_load_dword v96, v[38:39], off
	global_load_dword v97, v[36:37], off
	global_load_dword v98, v[34:35], off
	v_or_b32_e32 v36, s19, v1
	v_or_b32_e32 v34, s20, v2
	s_add_i32 s18, s18, 16
	s_add_i32 s17, s17, 16
	s_add_i32 s16, s16, -16
	v_mad_u64_u32 v[34:35], s[20:21], v34, s25, v[4:5]
	v_mad_u64_u32 v[36:37], s[20:21], v36, s25, v[4:5]
	v_or_b32_e32 v35, s22, v1
	v_or_b32_e32 v37, s23, v2
	v_or_b32_e32 v44, s26, v1
	v_or_b32_e32 v42, s27, v2
	v_or_b32_e32 v68, s39, v1
	v_or_b32_e32 v66, s40, v2
	v_or_b32_e32 v72, s41, v1
	v_or_b32_e32 v70, s42, v2
	v_or_b32_e32 v76, s43, v1
	v_or_b32_e32 v74, s44, v2
	v_or_b32_e32 v80, s45, v1
	v_or_b32_e32 v78, s46, v2
	v_or_b32_e32 v84, s47, v1
	v_or_b32_e32 v82, s48, v2
	s_cmp_lg_u32 s16, 0
	v_mad_u64_u32 v[38:39], s[20:21], v37, s25, v[4:5]
	v_mad_u64_u32 v[40:41], s[20:21], v35, s25, v[4:5]
	v_mad_u64_u32 v[42:43], s[20:21], v42, s25, v[4:5]
	v_mad_u64_u32 v[44:45], s[20:21], v44, s25, v[4:5]
	v_mad_u64_u32 v[66:67], s[20:21], v66, s25, v[4:5]
	v_mad_u64_u32 v[68:69], s[20:21], v68, s25, v[4:5]
	v_mad_u64_u32 v[70:71], s[20:21], v70, s25, v[4:5]
	v_mad_u64_u32 v[72:73], s[20:21], v72, s25, v[4:5]
	v_mad_u64_u32 v[74:75], s[20:21], v74, s25, v[4:5]
	v_mad_u64_u32 v[76:77], s[20:21], v76, s25, v[4:5]
	v_mad_u64_u32 v[78:79], s[20:21], v78, s25, v[4:5]
	v_mad_u64_u32 v[80:81], s[20:21], v80, s25, v[4:5]
	v_mad_u64_u32 v[82:83], s[20:21], v82, s25, v[4:5]
	v_mad_u64_u32 v[84:85], s[20:21], v84, s25, v[4:5]
	s_waitcnt vmcnt(15)
	ds_write_b32 v34, v33
	s_waitcnt vmcnt(14)
	ds_write_b32 v36, v65
	s_waitcnt vmcnt(13)
	ds_write_b32 v38, v86
	s_waitcnt vmcnt(12)
	ds_write_b32 v40, v87
	s_waitcnt vmcnt(4)
	ds_write_b32 v42, v95
	ds_write_b32 v44, v88
	ds_write_b32 v66, v94
	ds_write_b32 v68, v89
	s_waitcnt vmcnt(0)
	ds_write_b32 v70, v98
	ds_write_b32 v72, v90
	ds_write_b32 v74, v97
	ds_write_b32 v76, v91
	ds_write_b32 v78, v96
	ds_write_b32 v80, v92
	ds_write_b32 v82, v6
	ds_write_b32 v84, v93
	s_cbranch_scc1 .Lmy_lt_118

	s_waitcnt lgkmcnt(0)
	ds_read2_b32 v[28:29], v48 offset1:33
	s_waitcnt lgkmcnt(0)
	v_cvt_pk_bf16_f32 v34, v28, v29
	ds_read2_b32 v[28:29], v48 offset0:66 offset1:99
	s_waitcnt lgkmcnt(0)
	v_cvt_pk_bf16_f32 v35, v28, v29
	ds_read2_b32 v[28:29], v48 offset0:132 offset1:165
	v_lshlrev_b32_e32 v6, 1, v32
	v_or_b32_e32 v3, v31, v47
	s_waitcnt lgkmcnt(0)
	v_cvt_pk_bf16_f32 v36, v28, v29
	ds_read2_b32 v[28:29], v48 offset0:198 offset1:231
	v_lshl_add_u64 v[38:39], v[20:21], 0, v[6:7]
	v_lshlrev_b32_e32 v6, 9, v3
	s_waitcnt lgkmcnt(0)
	v_cvt_pk_bf16_f32 v37, v28, v29
	ds_read2_b32 v[28:29], v48 offset0:8 offset1:41
	v_lshl_add_u64 v[32:33], v[38:39], 0, v[6:7]
	global_store_dwordx4 v[32:33], v[34:37], off sc0 sc1
	s_waitcnt lgkmcnt(0)
	v_cvt_pk_bf16_f32 v32, v28, v29
	ds_read2_b32 v[28:29], v48 offset0:74 offset1:107
	s_waitcnt lgkmcnt(0)
	v_cvt_pk_bf16_f32 v33, v28, v29
	ds_read2_b32 v[28:29], v48 offset0:140 offset1:173
	v_or_b32_e32 v3, v31, v49
	s_waitcnt lgkmcnt(0)
	v_cvt_pk_bf16_f32 v34, v28, v29
	ds_read2_b32 v[28:29], v48 offset0:206 offset1:239
	v_lshlrev_b32_e32 v6, 9, v3
	s_waitcnt lgkmcnt(0)
	v_cvt_pk_bf16_f32 v35, v28, v29
	ds_read2_b32 v[28:29], v48 offset0:16 offset1:49
	v_lshl_add_u64 v[36:37], v[38:39], 0, v[6:7]
	global_store_dwordx4 v[36:37], v[32:35], off sc0 sc1
	v_or_b32_e32 v3, v31, v50
	v_lshlrev_b32_e32 v6, 9, v3
	s_waitcnt lgkmcnt(0)
	v_cvt_pk_bf16_f32 v32, v28, v29
	ds_read2_b32 v[28:29], v48 offset0:82 offset1:115
	s_waitcnt lgkmcnt(0)
	v_cvt_pk_bf16_f32 v33, v28, v29
	ds_read2_b32 v[28:29], v48 offset0:148 offset1:181
	s_waitcnt lgkmcnt(0)
	v_cvt_pk_bf16_f32 v34, v28, v29
	ds_read2_b32 v[28:29], v48 offset0:214 offset1:247
	s_waitcnt lgkmcnt(0)
	v_cvt_pk_bf16_f32 v35, v28, v29
	ds_read2_b32 v[28:29], v48 offset0:24 offset1:57
	v_lshl_add_u64 v[36:37], v[38:39], 0, v[6:7]
	global_store_dwordx4 v[36:37], v[32:35], off sc0 sc1
	s_waitcnt lgkmcnt(0)
	v_cvt_pk_bf16_f32 v28, v28, v29
	ds_read2_b32 v[32:33], v48 offset0:90 offset1:123
	s_waitcnt lgkmcnt(0)
	v_cvt_pk_bf16_f32 v29, v32, v33
	ds_read2_b32 v[32:33], v48 offset0:156 offset1:189
	v_or_b32_e32 v3, v31, v51
	s_waitcnt lgkmcnt(0)
	v_cvt_pk_bf16_f32 v30, v32, v33
	ds_read2_b32 v[32:33], v48 offset0:222 offset1:255
	v_lshlrev_b32_e32 v6, 9, v3
	s_waitcnt lgkmcnt(0)
	v_cvt_pk_bf16_f32 v31, v32, v33
	v_lshl_add_u64 v[32:33], v[38:39], 0, v[6:7]
	global_store_dwordx4 v[32:33], v[28:31], off sc0 sc1
	s_waitcnt lgkmcnt(0)

.Lmy_lt_123:

	s_lshl_b32 s18, s16, 1
	s_lshl_b32 s17, s15, 1
	v_or_b32_e32 v6, s18, v30
	s_add_i32 s21, s18, 4
	s_add_i32 s20, s17, 4
	s_add_i32 s22, s17, 8
	s_add_i32 s23, s18, 8
	v_lshlrev_b64 v[70:71], 12, v[6:7]
	v_or_b32_e32 v6, s21, v30
	v_mov_b32_e32 v35, v7
	v_mov_b32_e32 v37, v7
	v_mov_b32_e32 v39, v7
	v_or_b32_e32 v34, s17, v3
	s_add_i32 s26, s17, 12
	s_add_i32 s27, s18, 12
	s_add_i32 s39, s17, 16
	s_add_i32 s41, s17, 20
	s_add_i32 s43, s17, 24
	s_add_i32 s45, s17, 28
	v_or_b32_e32 v36, s20, v3
	v_or_b32_e32 v38, s22, v3
	v_lshlrev_b64 v[72:73], 12, v[6:7]
	v_or_b32_e32 v6, s23, v30
	v_mov_b32_e32 v41, v7
	v_mov_b32_e32 v43, v7
	v_mov_b32_e32 v45, v7
	v_mov_b32_e32 v67, v7
	v_mov_b32_e32 v69, v7
	s_add_i32 s40, s18, 16
	v_lshlrev_b64 v[34:35], 12, v[34:35]
	v_or_b32_e32 v40, s26, v3
	v_or_b32_e32 v42, s39, v3
	v_or_b32_e32 v44, s41, v3
	v_or_b32_e32 v66, s43, v3
	v_or_b32_e32 v68, s45, v3
	v_lshl_add_u64 v[70:71], v[28:29], 0, v[70:71]
	v_lshlrev_b64 v[36:37], 12, v[36:37]
	v_lshlrev_b64 v[38:39], 12, v[38:39]
	v_lshlrev_b64 v[74:75], 12, v[6:7]
	v_or_b32_e32 v6, s27, v30
	s_add_i32 s42, s18, 20
	v_lshl_add_u64 v[34:35], v[28:29], 0, v[34:35]
	v_lshlrev_b64 v[40:41], 12, v[40:41]
	v_lshlrev_b64 v[42:43], 12, v[42:43]
	v_lshlrev_b64 v[44:45], 12, v[44:45]
	v_lshlrev_b64 v[66:67], 12, v[66:67]
	v_lshlrev_b64 v[68:69], 12, v[68:69]
	v_lshl_add_u64 v[72:73], v[28:29], 0, v[72:73]
	v_lshl_add_u64 v[36:37], v[28:29], 0, v[36:37]
	v_lshl_add_u64 v[38:39], v[28:29], 0, v[38:39]
	global_load_dword v33, v[70:71], off
	global_load_dword v65, v[34:35], off
	v_lshlrev_b64 v[70:71], 12, v[6:7]
	v_or_b32_e32 v6, s40, v30
	s_add_i32 s44, s18, 24
	v_lshl_add_u64 v[40:41], v[28:29], 0, v[40:41]
	v_lshl_add_u64 v[42:43], v[28:29], 0, v[42:43]
	v_lshl_add_u64 v[44:45], v[28:29], 0, v[44:45]
	v_lshl_add_u64 v[66:67], v[28:29], 0, v[66:67]
	v_lshl_add_u64 v[68:69], v[28:29], 0, v[68:69]
	global_load_dword v86, v[72:73], off
	global_load_dword v87, v[36:37], off
	global_load_dword v88, v[38:39], off
	global_load_dword v89, v[40:41], off
	global_load_dword v90, v[42:43], off
	global_load_dword v91, v[44:45], off
	global_load_dword v92, v[66:67], off
	global_load_dword v93, v[68:69], off
	v_lshl_add_u64 v[36:37], v[28:29], 0, v[70:71]
	v_lshlrev_b64 v[38:39], 12, v[6:7]
	v_or_b32_e32 v6, s42, v30
	s_add_i32 s46, s18, 28
	v_lshl_add_u64 v[34:35], v[28:29], 0, v[74:75]
	global_load_dword v94, v[36:37], off
	global_load_dword v95, v[34:35], off
	v_lshlrev_b64 v[36:37], 12, v[6:7]
	v_or_b32_e32 v6, s44, v30
	v_lshl_add_u64 v[34:35], v[28:29], 0, v[38:39]
	v_lshlrev_b64 v[38:39], 12, v[6:7]
	v_or_b32_e32 v6, s46, v30
	v_lshlrev_b64 v[40:41], 12, v[6:7]
	v_lshl_add_u64 v[40:41], v[28:29], 0, v[40:41]
	v_lshl_add_u64 v[36:37], v[28:29], 0, v[36:37]
	v_lshl_add_u64 v[38:39], v[28:29], 0, v[38:39]
	global_load_dword v6, v[40:41], off
	global_load_dword v96, v[38:39], off
	global_load_dword v97, v[36:37], off
	global_load_dword v98, v[34:35], off
	v_or_b32_e32 v36, s17, v1
	v_or_b32_e32 v34, s18, v2
	s_add_i32 s16, s16, 16
	s_add_i32 s15, s15, 16
	s_add_i32 s14, s14, -16
	v_mad_u64_u32 v[34:35], s[18:19], v34, s25, v[4:5]
	v_mad_u64_u32 v[36:37], s[18:19], v36, s25, v[4:5]
	v_or_b32_e32 v35, s20, v1
	v_or_b32_e32 v37, s21, v2
	v_or_b32_e32 v44, s22, v1
	v_or_b32_e32 v42, s23, v2
	v_or_b32_e32 v68, s26, v1
	v_or_b32_e32 v66, s27, v2
	v_or_b32_e32 v72, s39, v1
	v_or_b32_e32 v70, s40, v2
	v_or_b32_e32 v76, s41, v1
	v_or_b32_e32 v74, s42, v2
	v_or_b32_e32 v80, s43, v1
	v_or_b32_e32 v78, s44, v2
	v_or_b32_e32 v84, s45, v1
	v_or_b32_e32 v82, s46, v2
	s_cmp_lg_u32 s14, 0
	v_mad_u64_u32 v[38:39], s[18:19], v37, s25, v[4:5]
	v_mad_u64_u32 v[40:41], s[18:19], v35, s25, v[4:5]
	v_mad_u64_u32 v[42:43], s[18:19], v42, s25, v[4:5]
	v_mad_u64_u32 v[44:45], s[18:19], v44, s25, v[4:5]
	v_mad_u64_u32 v[66:67], s[18:19], v66, s25, v[4:5]
	v_mad_u64_u32 v[68:69], s[18:19], v68, s25, v[4:5]
	v_mad_u64_u32 v[70:71], s[18:19], v70, s25, v[4:5]
	v_mad_u64_u32 v[72:73], s[18:19], v72, s25, v[4:5]
	v_mad_u64_u32 v[74:75], s[18:19], v74, s25, v[4:5]
	v_mad_u64_u32 v[76:77], s[18:19], v76, s25, v[4:5]
	v_mad_u64_u32 v[78:79], s[18:19], v78, s25, v[4:5]
	v_mad_u64_u32 v[80:81], s[18:19], v80, s25, v[4:5]
	v_mad_u64_u32 v[82:83], s[18:19], v82, s25, v[4:5]
	v_mad_u64_u32 v[84:85], s[18:19], v84, s25, v[4:5]
	s_waitcnt vmcnt(15)
	ds_write_b32 v34, v33
	s_waitcnt vmcnt(14)
	ds_write_b32 v36, v65
	s_waitcnt vmcnt(13)
	ds_write_b32 v38, v86
	s_waitcnt vmcnt(12)
	ds_write_b32 v40, v87
	s_waitcnt vmcnt(4)
	ds_write_b32 v42, v95
	ds_write_b32 v44, v88
	ds_write_b32 v66, v94
	ds_write_b32 v68, v89
	s_waitcnt vmcnt(0)
	ds_write_b32 v70, v98
	ds_write_b32 v72, v90
	ds_write_b32 v74, v97
	ds_write_b32 v76, v91
	ds_write_b32 v78, v96
	ds_write_b32 v80, v92
	ds_write_b32 v82, v6
	ds_write_b32 v84, v93
	s_cbranch_scc1 .Lmy_lt_123

	s_waitcnt lgkmcnt(0)
	ds_read2_b32 v[28:29], v48 offset1:33
	v_and_b32_e32 v3, 0x1e0, v32
	v_lshlrev_b32_e32 v6, 1, v31
	s_waitcnt lgkmcnt(0)
	v_cvt_pk_bf16_f32 v28, v28, v29
	ds_read2_b32 v[34:35], v48 offset0:66 offset1:99
	v_lshl_add_u64 v[32:33], v[22:23], 0, v[6:7]
	v_or_b32_e32 v6, v3, v47
	s_waitcnt lgkmcnt(0)
	v_cvt_pk_bf16_f32 v29, v34, v35
	ds_read2_b32 v[34:35], v48 offset0:132 offset1:165
	v_lshlrev_b32_e32 v6, 9, v6
	s_waitcnt lgkmcnt(0)
	v_cvt_pk_bf16_f32 v30, v34, v35
	ds_read2_b32 v[34:35], v48 offset0:198 offset1:231
	s_waitcnt lgkmcnt(0)
	v_cvt_pk_bf16_f32 v31, v34, v35
	v_lshl_add_u64 v[36:37], v[32:33], 0, v[6:7]
	ds_read2_b32 v[34:35], v48 offset0:8 offset1:41
	global_store_dwordx4 v[36:37], v[28:31], off sc0 sc1
	v_or_b32_e32 v6, v3, v49
	v_lshlrev_b32_e32 v6, 9, v6
	s_waitcnt lgkmcnt(0)
	v_cvt_pk_bf16_f32 v28, v34, v35
	ds_read2_b32 v[30:31], v48 offset0:74 offset1:107
	s_waitcnt lgkmcnt(0)
	v_cvt_pk_bf16_f32 v29, v30, v31
	ds_read2_b32 v[30:31], v48 offset0:140 offset1:173
	s_waitcnt lgkmcnt(0)
	v_cvt_pk_bf16_f32 v30, v30, v31
	ds_read2_b32 v[34:35], v48 offset0:206 offset1:239
	s_waitcnt lgkmcnt(0)
	v_cvt_pk_bf16_f32 v31, v34, v35
	v_lshl_add_u64 v[36:37], v[32:33], 0, v[6:7]
	ds_read2_b32 v[34:35], v48 offset0:16 offset1:49
	global_store_dwordx4 v[36:37], v[28:31], off sc0 sc1
	v_or_b32_e32 v6, v3, v50
	v_lshlrev_b32_e32 v6, 9, v6
	s_waitcnt lgkmcnt(0)
	v_cvt_pk_bf16_f32 v28, v34, v35
	ds_read2_b32 v[30:31], v48 offset0:82 offset1:115
	s_waitcnt lgkmcnt(0)
	v_cvt_pk_bf16_f32 v29, v30, v31
	ds_read2_b32 v[30:31], v48 offset0:148 offset1:181
	s_waitcnt lgkmcnt(0)
	v_cvt_pk_bf16_f32 v30, v30, v31
	ds_read2_b32 v[34:35], v48 offset0:214 offset1:247
	s_waitcnt lgkmcnt(0)
	v_cvt_pk_bf16_f32 v31, v34, v35
	v_lshl_add_u64 v[36:37], v[32:33], 0, v[6:7]
	v_or_b32_e32 v3, v3, v51
	ds_read2_b32 v[34:35], v48 offset0:24 offset1:57
	global_store_dwordx4 v[36:37], v[28:31], off sc0 sc1
	v_lshlrev_b32_e32 v6, 9, v3
	v_lshl_add_u64 v[32:33], v[32:33], 0, v[6:7]
	s_waitcnt lgkmcnt(0)
	v_cvt_pk_bf16_f32 v28, v34, v35
	ds_read2_b32 v[30:31], v48 offset0:90 offset1:123
	s_waitcnt lgkmcnt(0)
	v_cvt_pk_bf16_f32 v29, v30, v31
	ds_read2_b32 v[30:31], v48 offset0:156 offset1:189
	s_waitcnt lgkmcnt(0)
	v_cvt_pk_bf16_f32 v30, v30, v31
	ds_read2_b32 v[34:35], v48 offset0:222 offset1:255
	s_waitcnt lgkmcnt(0)
	v_cvt_pk_bf16_f32 v31, v34, v35
	global_store_dwordx4 v[32:33], v[28:31], off sc0 sc1
	s_waitcnt lgkmcnt(0)

.Lmy_lt_128:

	s_lshl_b32 s15, s12, 1
	s_lshl_b32 s18, s13, 1
	v_or_b32_e32 v32, s18, v6
	s_add_i32 s19, s15, 4
	s_add_i32 s20, s18, 4
	s_add_i32 s21, s15, 8
	s_add_i32 s22, s18, 8
	s_add_i32 s23, s15, 12
	s_add_i32 s26, s18, 12
	s_add_i32 s27, s15, 16
	s_add_i32 s39, s18, 16
	s_add_i32 s40, s15, 20
	s_add_i32 s41, s18, 20
	s_add_i32 s42, s15, 24
	s_add_i32 s43, s18, 24
	s_add_i32 s44, s15, 28
	s_add_i32 s45, s18, 28
	v_or_b32_e32 v34, s15, v3
	v_mad_u64_u32 v[32:33], s[16:17], v32, s37, v[28:29]
	v_or_b32_e32 v38, s19, v3
	v_or_b32_e32 v36, s20, v6
	v_or_b32_e32 v42, s21, v3
	v_or_b32_e32 v40, s22, v6
	v_or_b32_e32 v65, s23, v3
	v_or_b32_e32 v44, s26, v6
	v_or_b32_e32 v70, s27, v3
	v_or_b32_e32 v68, s39, v6
	v_or_b32_e32 v74, s40, v3
	v_or_b32_e32 v72, s41, v6
	v_or_b32_e32 v78, s42, v3
	v_or_b32_e32 v76, s43, v6
	v_or_b32_e32 v82, s44, v3
	v_or_b32_e32 v80, s45, v6
	v_mad_u64_u32 v[34:35], s[16:17], v34, s37, v[28:29]
	v_mad_u64_u32 v[36:37], s[16:17], v36, s37, v[28:29]
	v_mad_u64_u32 v[38:39], s[16:17], v38, s37, v[28:29]
	v_mad_u64_u32 v[40:41], s[16:17], v40, s37, v[28:29]
	v_mad_u64_u32 v[42:43], s[16:17], v42, s37, v[28:29]
	v_mad_u64_u32 v[44:45], s[16:17], v44, s37, v[28:29]
	v_mad_u64_u32 v[66:67], s[16:17], v65, s37, v[28:29]
	v_mad_u64_u32 v[68:69], s[16:17], v68, s37, v[28:29]
	v_mad_u64_u32 v[70:71], s[16:17], v70, s37, v[28:29]
	v_mad_u64_u32 v[72:73], s[16:17], v72, s37, v[28:29]
	v_mad_u64_u32 v[74:75], s[16:17], v74, s37, v[28:29]
	v_mad_u64_u32 v[76:77], s[16:17], v76, s37, v[28:29]
	v_mad_u64_u32 v[78:79], s[16:17], v78, s37, v[28:29]
	v_mad_u64_u32 v[80:81], s[16:17], v80, s37, v[28:29]
	v_mad_u64_u32 v[82:83], s[16:17], v82, s37, v[28:29]
	global_load_dword v65, v[32:33], off
	global_load_dword v84, v[34:35], off
	global_load_dword v85, v[36:37], off
	global_load_dword v86, v[38:39], off
	global_load_dword v87, v[40:41], off
	global_load_dword v88, v[42:43], off
	global_load_dword v89, v[44:45], off
	global_load_dword v90, v[66:67], off
	global_load_dword v91, v[68:69], off
	global_load_dword v92, v[70:71], off
	global_load_dword v93, v[72:73], off
	global_load_dword v94, v[74:75], off
	global_load_dword v95, v[76:77], off
	global_load_dword v96, v[78:79], off
	global_load_dword v97, v[80:81], off
	global_load_dword v98, v[82:83], off
	v_or_b32_e32 v34, s15, v1
	v_or_b32_e32 v32, s18, v2
	s_add_i32 s13, s13, 16
	s_add_i32 s12, s12, 16
	s_add_i32 s14, s14, -16
	v_mad_u64_u32 v[32:33], s[16:17], v32, s25, v[4:5]
	v_mad_u64_u32 v[34:35], s[16:17], v34, s25, v[4:5]
	v_or_b32_e32 v33, s19, v1
	v_or_b32_e32 v35, s20, v2
	v_or_b32_e32 v42, s21, v1
	v_or_b32_e32 v40, s22, v2
	v_or_b32_e32 v66, s23, v1
	v_or_b32_e32 v44, s26, v2
	v_or_b32_e32 v70, s27, v1
	v_or_b32_e32 v68, s39, v2
	v_or_b32_e32 v74, s40, v1
	v_or_b32_e32 v72, s41, v2
	v_or_b32_e32 v78, s42, v1
	v_or_b32_e32 v76, s43, v2
	v_or_b32_e32 v82, s44, v1
	v_or_b32_e32 v80, s45, v2
	s_cmp_lg_u32 s14, 0
	v_mad_u64_u32 v[36:37], s[16:17], v35, s25, v[4:5]
	v_mad_u64_u32 v[38:39], s[16:17], v33, s25, v[4:5]
	v_mad_u64_u32 v[40:41], s[16:17], v40, s25, v[4:5]
	v_mad_u64_u32 v[42:43], s[16:17], v42, s25, v[4:5]
	v_mad_u64_u32 v[44:45], s[16:17], v44, s25, v[4:5]
	v_mad_u64_u32 v[66:67], s[16:17], v66, s25, v[4:5]
	v_mad_u64_u32 v[68:69], s[16:17], v68, s25, v[4:5]
	v_mad_u64_u32 v[70:71], s[16:17], v70, s25, v[4:5]
	v_mad_u64_u32 v[72:73], s[16:17], v72, s25, v[4:5]
	v_mad_u64_u32 v[74:75], s[16:17], v74, s25, v[4:5]
	v_mad_u64_u32 v[76:77], s[16:17], v76, s25, v[4:5]
	v_mad_u64_u32 v[78:79], s[16:17], v78, s25, v[4:5]
	v_mad_u64_u32 v[80:81], s[16:17], v80, s25, v[4:5]
	v_mad_u64_u32 v[82:83], s[16:17], v82, s25, v[4:5]
	s_waitcnt vmcnt(15)
	ds_write_b32 v32, v65
	s_waitcnt vmcnt(14)
	ds_write_b32 v34, v84
	s_waitcnt vmcnt(13)
	ds_write_b32 v36, v85
	s_waitcnt vmcnt(12)
	ds_write_b32 v38, v86
	s_waitcnt vmcnt(11)
	ds_write_b32 v40, v87
	s_waitcnt vmcnt(10)
	ds_write_b32 v42, v88
	s_waitcnt vmcnt(9)
	ds_write_b32 v44, v89
	s_waitcnt vmcnt(8)
	ds_write_b32 v66, v90
	s_waitcnt vmcnt(7)
	ds_write_b32 v68, v91
	s_waitcnt vmcnt(6)
	ds_write_b32 v70, v92
	s_waitcnt vmcnt(5)
	ds_write_b32 v72, v93
	s_waitcnt vmcnt(4)
	ds_write_b32 v74, v94
	s_waitcnt vmcnt(3)
	ds_write_b32 v76, v95
	s_waitcnt vmcnt(2)
	ds_write_b32 v78, v96
	s_waitcnt vmcnt(1)
	ds_write_b32 v80, v97
	s_waitcnt vmcnt(0)
	ds_write_b32 v82, v98
	s_cbranch_scc1 .Lmy_lt_128

	s_waitcnt lgkmcnt(0)
	ds_read2_b32 v[28:29], v48 offset1:33
	s_waitcnt lgkmcnt(0)
	v_cvt_pk_bf16_f32 v32, v28, v29
	ds_read2_b32 v[28:29], v48 offset0:66 offset1:99
	v_or_b32_e32 v3, v30, v47
	s_waitcnt lgkmcnt(0)
	v_cvt_pk_bf16_f32 v33, v28, v29
	ds_read2_b32 v[28:29], v48 offset0:132 offset1:165
	v_lshlrev_b32_e32 v6, 1, v31
	v_mul_u32_u24_e32 v3, 0x180, v3
	s_waitcnt lgkmcnt(0)
	v_cvt_pk_bf16_f32 v34, v28, v29
	ds_read2_b32 v[28:29], v48 offset0:198 offset1:231
	v_lshl_add_u64 v[36:37], v[24:25], 0, v[6:7]
	v_lshlrev_b32_e32 v6, 1, v3
	s_waitcnt lgkmcnt(0)
	v_cvt_pk_bf16_f32 v35, v28, v29
	ds_read2_b32 v[28:29], v48 offset0:8 offset1:41
	v_lshl_add_u64 v[38:39], v[36:37], 0, v[6:7]
	global_store_dwordx4 v[38:39], v[32:35], off sc0 sc1
	v_or_b32_e32 v3, v30, v49
	v_mul_u32_u24_e32 v3, 0x180, v3
	s_waitcnt lgkmcnt(0)
	v_cvt_pk_bf16_f32 v32, v28, v29
	ds_read2_b32 v[28:29], v48 offset0:74 offset1:107
	s_waitcnt lgkmcnt(0)
	v_cvt_pk_bf16_f32 v33, v28, v29
	ds_read2_b32 v[28:29], v48 offset0:140 offset1:173
	s_waitcnt lgkmcnt(0)
	v_cvt_pk_bf16_f32 v34, v28, v29
	ds_read2_b32 v[28:29], v48 offset0:206 offset1:239
	v_lshlrev_b32_e32 v6, 1, v3
	s_waitcnt lgkmcnt(0)
	v_cvt_pk_bf16_f32 v35, v28, v29
	ds_read2_b32 v[28:29], v48 offset0:16 offset1:49
	v_lshl_add_u64 v[38:39], v[36:37], 0, v[6:7]
	global_store_dwordx4 v[38:39], v[32:35], off sc0 sc1
	v_or_b32_e32 v3, v30, v50
	v_mul_u32_u24_e32 v3, 0x180, v3
	s_waitcnt lgkmcnt(0)
	v_cvt_pk_bf16_f32 v32, v28, v29
	ds_read2_b32 v[28:29], v48 offset0:82 offset1:115
	s_waitcnt lgkmcnt(0)
	v_cvt_pk_bf16_f32 v33, v28, v29
	ds_read2_b32 v[28:29], v48 offset0:148 offset1:181
	s_waitcnt lgkmcnt(0)
	v_cvt_pk_bf16_f32 v34, v28, v29
	ds_read2_b32 v[28:29], v48 offset0:214 offset1:247
	v_lshlrev_b32_e32 v6, 1, v3
	s_waitcnt lgkmcnt(0)
	v_cvt_pk_bf16_f32 v35, v28, v29
	ds_read2_b32 v[28:29], v48 offset0:24 offset1:57
	v_lshl_add_u64 v[38:39], v[36:37], 0, v[6:7]
	global_store_dwordx4 v[38:39], v[32:35], off sc0 sc1
	v_or_b32_e32 v3, v30, v51
	v_mul_u32_u24_e32 v3, 0x180, v3
	s_waitcnt lgkmcnt(0)
	v_cvt_pk_bf16_f32 v32, v28, v29
	ds_read2_b32 v[28:29], v48 offset0:90 offset1:123
	s_waitcnt lgkmcnt(0)
	v_cvt_pk_bf16_f32 v33, v28, v29
	ds_read2_b32 v[28:29], v48 offset0:156 offset1:189
	s_waitcnt lgkmcnt(0)
	v_cvt_pk_bf16_f32 v34, v28, v29
	ds_read2_b32 v[28:29], v48 offset0:222 offset1:255
	v_lshlrev_b32_e32 v6, 1, v3
	s_waitcnt lgkmcnt(0)
	v_cvt_pk_bf16_f32 v35, v28, v29
	v_lshl_add_u64 v[28:29], v[36:37], 0, v[6:7]
	global_store_dwordx4 v[28:29], v[32:35], off sc0 sc1
	s_waitcnt lgkmcnt(0)
